# gdn-prep: D1 substitution reads pipelined 2 rows ahead + packed f32 mul/add peephole in step A + DPP butterflies for 4 of 5 l2norm rounds; on top of modpipe
# speedup vs baseline: 1.0011x; 1.0011x over previous
; #define LAS __attribute__((address_space(3)))
; __device__ __forceinline__ void gdn_prep_phase(const Frame& F0, const Args& a0, int l) {
;     const Frame F = relaunder(F0); const Args a = relaunder_args(a0);
;     const bf16* Z = (const bf16*)(a.ws + WS_Z); const float* AB = (const float*)(a.ws + WS_AB);
;     const float* convw = a.in[I_CONVW] + (size_t)l * 5 * 3072; const float* alog = a.in[I_ALOG] + l * 16; const float* dtb = a.in[I_DTB] + l * 16;
;     unsigned char* RECB = a.ws + WS_GREC; float* UB = (float*)(a.ws + WS_GU); float* GLB = (float*)(a.ws + WS_GL);
;     LAS unsigned char* lds = F.lds + RING_OFF;
;     const int tid = F.tid, lane = F.lane, wave = F.wave;
;     LAS float* gcs = (LAS float*)(lds + GD_GATES); LAS float* bts = gcs + 128; LAS float* egs = gcs + 256; LAS float* ekd = gcs + 384;
;     v2u zr[20]; f32x4 cw[5]; float pab0 = 0.f, pab1 = 0.f;
;     ...
;     if (F.vcu < NB * 8 * 36) GD_PREFETCH(F.vcu);
;     for (int u = F.vcu; u < NB * 8 * 36; u += F.G) {
.LBB0_372:
	s_cmp_le_i32 s64, s18
	s_cselect_b64 s[0:1], -1, 0
	s_and_b64 s[30:31], s[0:1], s[2:3]
	s_andn2_b64 vcc, exec, s[30:31]
	s_cbranch_vccnz .LBB0_513
	v_mov_b32_e32 v222, 0xbfb8aa3b
	v_mov_b32_e32 v223, 0xbfb8aa3b
	s_and_b32 s27, s93, 31
	s_mul_i32 s27, s27, 36
	s_lshr_b32 s98, s93, 5
	s_add_i32 s27, s27, s98
	s_cmpk_lt_i32 s93, 0x80
	s_cselect_b32 s98, 40, 32
	s_add_i32 s98, s98, s27
	s_mov_b32 s0, s94
	s_mov_b32 s14, s95
	s_mov_b32 s22, 8
	v_readlane_b32 s48, v221, 0
	s_waitcnt vmcnt(0)
	v_mbcnt_lo_u32_b32 v22, -1, 0
	v_mbcnt_hi_u32_b32 v22, -1, v22
	v_readlane_b32 s49, v221, 1
	s_mov_b64 s[0:1], s[48:49]
	v_readlane_b32 s50, v221, 2
	v_readlane_b32 s51, v221, 3
	s_mov_b64 s[0:1], s[50:51]
	v_readlane_b32 s52, v221, 4
	v_readlane_b32 s53, v221, 5
	s_mov_b64 s[0:1], s[52:53]
	v_readlane_b32 s54, v221, 6
	v_readlane_b32 s55, v221, 7
	s_mov_b64 s[0:1], s[54:55]
	v_readlane_b32 s56, v221, 8
	v_readlane_b32 s57, v221, 9
	s_mov_b64 s[0:1], s[56:57]
	v_readlane_b32 s58, v221, 10
	v_readlane_b32 s59, v221, 11
	s_mov_b64 s[0:1], s[58:59]
	v_readlane_b32 s60, v221, 12
	v_readlane_b32 s61, v221, 13
	s_mov_b64 s[0:1], s[60:61]
	v_readlane_b32 s62, v221, 14
	v_readlane_b32 s63, v221, 15
	s_mov_b64 s[0:1], s[62:63]
	v_readlane_b32 s64, v221, 16
	v_readlane_b32 s65, v221, 17
	v_readlane_b32 s66, v221, 18
	v_readlane_b32 s67, v221, 19
	v_readlane_b32 s68, v221, 20
	v_readlane_b32 s69, v221, 21
	v_readlane_b32 s70, v221, 22
	v_readlane_b32 s71, v221, 23
	s_mov_b64 s[2:3], s[64:65]
	s_mov_b64 s[6:7], s[66:67]
	s_mov_b64 s[8:9], s[68:69]
	s_mov_b64 s[0:1], s[70:71]
	v_readlane_b32 s72, v221, 24
	v_readlane_b32 s73, v221, 25
	s_mov_b64 s[0:1], s[72:73]
	v_readlane_b32 s74, v221, 26
	v_readlane_b32 s75, v221, 27
	s_mov_b64 s[0:1], s[74:75]
	v_readlane_b32 s76, v221, 28
	v_readlane_b32 s77, v221, 29
	s_mov_b64 s[0:1], s[76:77]
	v_readlane_b32 s78, v221, 30
	v_readlane_b32 s79, v221, 31
	s_mov_b64 s[0:1], s[78:79]
	s_mov_b64 s[0:1], s[40:41]
	s_mov_b64 s[0:1], s[42:43]
	s_mov_b64 s[0:1], s[44:45]
	s_mov_b64 s[10:11], s[46:47]
	s_add_u32 s76, s10, 0x1ec00000
	s_addc_u32 s77, s11, 0
	s_add_u32 s0, s10, 0x25400000
	s_mul_i32 s5, s24, 0xf000
	s_addc_u32 s1, s11, 0
	s_mul_hi_u32 s4, s24, 0xf000
	s_add_u32 s62, s2, s5
	s_addc_u32 s63, s3, s4
	s_cmp_lt_i32 s27, s98
	v_mov_b32_e32 v129, 0
	s_cselect_b64 s[12:13], -1, 0
	s_cmp_ge_i32 s27, s98
	v_mov_b32_e32 v130, 0
	s_cbranch_scc1 .LBB0_395
	s_cmp_lt_i32 s14, 4
	v_mbcnt_lo_u32_b32 v23, -1, 0
	v_mbcnt_hi_u32_b32 v23, -1, v23
	s_cselect_b64 s[2:3], -1, 0
	s_cmp_gt_i32 s14, 3
	v_ashrrev_i32_e32 v0, 5, v23
	s_mov_b64 s[4:5], -1
	s_cbranch_scc0 .LBB0_376
	s_lshl_b32 s4, s14, 1
	s_add_i32 s4, s4, -8
	v_add_lshl_u32 v24, s4, v0, 3
	s_mov_b64 s[4:5], 0

; #define LDS_BARRIER() asm volatile("s_waitcnt lgkmcnt(0)\n\ts_barrier" ::: "memory")
; __device__ __forceinline__ void gdn_prep_phase(const Frame& F0, const Args& a0, int l) {
;     ...
;         LDS_BARRIER();
;         int ta_; asm volatile("v_mbcnt_lo_u32_b32 %0, -1, 0\n\tv_mbcnt_hi_u32_b32 %0, -1, %0" : "=v"(ta_));
;     ...
;         { const int q4 = ta_ & 31;
;           if (wave < 4) { const int part = ta_ >> 5, r0 = 16 * wave; GD_CONV(16, true); }
;           else { const int part = 2, r0 = 8 * (2 * (wave - 4) + (ta_ >> 5)); GD_CONV(8, false); } }
.LBB0_398:
	s_mul_hi_i32 s10, s27, 0x38e38e39
	s_lshr_b32 s11, s10, 31
	s_ashr_i32 s12, s10, 3
	s_add_i32 s12, s12, s11
	s_waitcnt lgkmcnt(0)
	s_barrier
	s_mul_i32 s8, s12, 0xffffffdc
	v_mbcnt_lo_u32_b32 v133, -1, 0
	v_mbcnt_hi_u32_b32 v133, -1, v133
	s_add_i32 s88, s27, s8
	v_and_b32_e32 v20, 31, v133
	v_ashrrev_i32_e32 v131, 5, v133
	s_mov_b64 s[8:9], -1
	s_and_b64 vcc, exec, s[34:35]
	s_mul_i32 s13, s12, 0xfffff700
	v_lshlrev_b32_e32 v132, 3, v20
	s_waitcnt vmcnt(11)
	v_lshlrev_b32_e32 v36, 16, v72
	v_and_b32_e32 v37, 0xffff0000, v72
	v_lshlrev_b32_e32 v42, 16, v73
	v_and_b32_e32 v43, 0xffff0000, v73
	s_waitcnt vmcnt(10)
	v_lshlrev_b32_e32 v44, 16, v74
	v_and_b32_e32 v45, 0xffff0000, v74
	v_lshlrev_b32_e32 v46, 16, v75
	v_and_b32_e32 v47, 0xffff0000, v75
	s_waitcnt vmcnt(9)
	v_lshlrev_b32_e32 v52, 16, v84
	v_and_b32_e32 v53, 0xffff0000, v84
	v_lshlrev_b32_e32 v54, 16, v85
	v_and_b32_e32 v55, 0xffff0000, v85
	s_waitcnt vmcnt(8)
	v_lshlrev_b32_e32 v56, 16, v86
	v_and_b32_e32 v57, 0xffff0000, v86
	v_lshlrev_b32_e32 v58, 16, v87
	v_and_b32_e32 v59, 0xffff0000, v87
	s_waitcnt vmcnt(7)
	v_lshlrev_b32_e32 v48, 16, v88
	v_and_b32_e32 v49, 0xffff0000, v88
	v_lshlrev_b32_e32 v50, 16, v89
	v_and_b32_e32 v51, 0xffff0000, v89
	s_waitcnt vmcnt(6)
	v_lshlrev_b32_e32 v38, 16, v90
	v_and_b32_e32 v39, 0xffff0000, v90
	v_lshlrev_b32_e32 v40, 16, v91
	v_and_b32_e32 v41, 0xffff0000, v91
	s_waitcnt vmcnt(5)
	v_lshlrev_b32_e32 v30, 16, v96
	v_and_b32_e32 v31, 0xffff0000, v96
	v_lshlrev_b32_e32 v32, 16, v97
	v_and_b32_e32 v33, 0xffff0000, v97
	s_waitcnt vmcnt(4)
	v_lshlrev_b32_e32 v20, 16, v98
	v_and_b32_e32 v21, 0xffff0000, v98
	v_lshlrev_b32_e32 v22, 16, v99
	v_and_b32_e32 v23, 0xffff0000, v99
	s_cbranch_vccz .LBB0_400
	s_add_i32 s8, s45, s13
	s_add_i32 s9, s8, 0xffffff00
	s_cmp_lt_i32 s88, 4
	v_add_u32_e32 v122, s73, v131
	s_cselect_b32 s8, s8, s9
	v_lshl_add_u32 v24, v122, 3, s8
	v_cmp_eq_u32_e32 vcc, 0, v24
	v_pk_fma_f32 v[110:111], v[0:1], v[36:37], 0 op_sel_hi:[1,1,0]
	v_pk_fma_f32 v[114:115], v[0:1], v[44:45], 0 op_sel_hi:[1,1,0]
	v_cndmask_b32_e64 v64, v106, 0, vcc
	v_cndmask_b32_e64 v66, v104, 0, vcc
	v_lshlrev_b32_e32 v28, 16, v64
	v_and_b32_e32 v29, 0xffff0000, v64
	v_pk_fma_f32 v[28:29], v[0:1], v[28:29], 0 op_sel_hi:[1,1,0]
	v_lshlrev_b32_e32 v60, 16, v66
	v_and_b32_e32 v61, 0xffff0000, v66
	v_pk_fma_f32 v[28:29], v[4:5], v[60:61], v[28:29]
	v_cndmask_b32_e64 v65, v107, 0, vcc
	v_pk_fma_f32 v[28:29], v[8:9], v[36:37], v[28:29]
	v_cndmask_b32_e64 v67, v105, 0, vcc
	v_pk_fma_f32 v[28:29], v[12:13], v[44:45], v[28:29]
	v_lshlrev_b32_e32 v34, 16, v65
	v_pk_fma_f32 v[28:29], v[16:17], v[52:53], v[28:29]
	v_and_b32_e32 v35, 0xffff0000, v65
	v_pk_mul_f32 v[108:109], v[28:29], v[222:223] op_sel_hi:[1,0]
	v_exp_f32_e32 v108, v108
	v_exp_f32_e32 v109, v109
	v_pk_fma_f32 v[34:35], v[2:3], v[34:35], 0 op_sel_hi:[1,1,0]
	v_lshlrev_b32_e32 v62, 16, v67
	v_and_b32_e32 v63, 0xffff0000, v67
	v_pk_add_f32 v[108:109], v[108:109], 1.0 op_sel_hi:[1,0]
	v_pk_fma_f32 v[34:35], v[6:7], v[62:63], v[34:35]
	v_rcp_f32_e32 v108, v108
	v_rcp_f32_e32 v109, v109
	v_pk_fma_f32 v[34:35], v[10:11], v[42:43], v[34:35]
	v_pk_fma_f32 v[60:61], v[0:1], v[60:61], 0 op_sel_hi:[1,1,0]
	v_pk_fma_f32 v[34:35], v[14:15], v[46:47], v[34:35]
	v_pk_mul_f32 v[28:29], v[28:29], v[108:109]
	v_pk_fma_f32 v[34:35], v[18:19], v[54:55], v[34:35]
	v_pk_fma_f32 v[60:61], v[4:5], v[36:37], v[60:61]
	v_pk_mul_f32 v[108:109], v[34:35], v[222:223] op_sel_hi:[1,0]
	v_exp_f32_e32 v108, v108
	v_exp_f32_e32 v109, v109
	v_pk_fma_f32 v[60:61], v[8:9], v[44:45], v[60:61]
	v_pk_fma_f32 v[62:63], v[2:3], v[62:63], 0 op_sel_hi:[1,1,0]
	v_pk_add_f32 v[108:109], v[108:109], 1.0 op_sel_hi:[1,0]
	v_rcp_f32_e32 v108, v108
	v_rcp_f32_e32 v109, v109
	v_pk_fma_f32 v[60:61], v[12:13], v[52:53], v[60:61]
	v_pk_fma_f32 v[62:63], v[6:7], v[42:43], v[62:63]
	v_pk_fma_f32 v[60:61], v[16:17], v[56:57], v[60:61]
	v_pk_mul_f32 v[34:35], v[34:35], v[108:109]
	v_pk_mul_f32 v[108:109], v[60:61], v[222:223] op_sel_hi:[1,0]
	v_exp_f32_e32 v108, v108
	v_exp_f32_e32 v109, v109
	v_pk_fma_f32 v[62:63], v[10:11], v[46:47], v[62:63]
	v_pk_fma_f32 v[110:111], v[4:5], v[44:45], v[110:111]
	v_pk_add_f32 v[108:109], v[108:109], 1.0 op_sel_hi:[1,0]
	v_rcp_f32_e32 v108, v108
	v_rcp_f32_e32 v109, v109
	v_pk_fma_f32 v[62:63], v[14:15], v[54:55], v[62:63]
	v_pk_fma_f32 v[110:111], v[8:9], v[52:53], v[110:111]
	v_pk_fma_f32 v[62:63], v[18:19], v[58:59], v[62:63]
	v_pk_mul_f32 v[60:61], v[60:61], v[108:109]
	v_pk_mul_f32 v[108:109], v[62:63], v[222:223] op_sel_hi:[1,0]
	v_exp_f32_e32 v108, v108
	v_exp_f32_e32 v109, v109
	v_pk_fma_f32 v[110:111], v[12:13], v[56:57], v[110:111]
	v_pk_fma_f32 v[114:115], v[4:5], v[52:53], v[114:115]
	v_pk_add_f32 v[108:109], v[108:109], 1.0 op_sel_hi:[1,0]
	v_rcp_f32_e32 v108, v108
	v_rcp_f32_e32 v109, v109
	v_pk_fma_f32 v[114:115], v[8:9], v[56:57], v[114:115]
	v_pk_fma_f32 v[118:119], v[0:1], v[52:53], 0 op_sel_hi:[1,1,0]
	v_pk_fma_f32 v[114:115], v[12:13], v[48:49], v[114:115]
	v_pk_mul_f32 v[62:63], v[62:63], v[108:109]
	v_pk_fma_f32 v[108:109], v[2:3], v[42:43], 0 op_sel_hi:[1,1,0]
	v_pk_fma_f32 v[118:119], v[4:5], v[56:57], v[118:119]
	v_pk_fma_f32 v[108:109], v[6:7], v[46:47], v[108:109]
	v_pk_fma_f32 v[118:119], v[8:9], v[48:49], v[118:119]
	v_pk_fma_f32 v[108:109], v[10:11], v[54:55], v[108:109]
	v_pk_fma_f32 v[118:119], v[12:13], v[38:39], v[118:119]
	v_pk_fma_f32 v[108:109], v[14:15], v[58:59], v[108:109]
	v_pk_fma_f32 v[124:125], v[0:1], v[56:57], 0 op_sel_hi:[1,1,0]
	v_pk_fma_f32 v[112:113], v[18:19], v[50:51], v[108:109]
	v_pk_fma_f32 v[108:109], v[16:17], v[48:49], v[110:111]
	v_pk_fma_f32 v[124:125], v[4:5], v[48:49], v[124:125]
	v_pk_mul_f32 v[110:111], v[108:109], v[222:223] op_sel_hi:[1,0]
	v_exp_f32_e32 v110, v110
	v_exp_f32_e32 v111, v111
	v_pk_fma_f32 v[124:125], v[8:9], v[38:39], v[124:125]
	s_movk_i32 s8, 0xf8
	v_pk_add_f32 v[110:111], v[110:111], 1.0 op_sel_hi:[1,0]
	v_rcp_f32_e32 v110, v110
	v_rcp_f32_e32 v111, v111
	v_pk_fma_f32 v[124:125], v[12:13], v[30:31], v[124:125]
	s_cselect_b32 s8, s8, 0x7f8
	v_pk_fma_f32 v[134:135], v[0:1], v[48:49], 0 op_sel_hi:[1,1,0]
	v_pk_mul_f32 v[108:109], v[108:109], v[110:111]
	v_pk_mul_f32 v[110:111], v[112:113], v[222:223] op_sel_hi:[1,0]
	v_exp_f32_e32 v110, v110
	v_exp_f32_e32 v111, v111
	v_cmp_eq_u32_e32 vcc, s8, v24
	v_pk_fma_f32 v[134:135], v[4:5], v[38:39], v[134:135]
	v_pk_add_f32 v[110:111], v[110:111], 1.0 op_sel_hi:[1,0]
	v_rcp_f32_e32 v110, v110
	v_rcp_f32_e32 v111, v111
	s_waitcnt vmcnt(3)
	v_cndmask_b32_e64 v24, v100, 0, vcc
	v_pk_fma_f32 v[134:135], v[8:9], v[30:31], v[134:135]
	v_lshlrev_b32_e32 v136, 16, v24
	v_pk_mul_f32 v[110:111], v[112:113], v[110:111]
	v_pk_fma_f32 v[112:113], v[2:3], v[46:47], 0 op_sel_hi:[1,1,0]
	v_pk_fma_f32 v[134:135], v[12:13], v[20:21], v[134:135]
	v_pk_fma_f32 v[112:113], v[6:7], v[54:55], v[112:113]
	v_and_b32_e32 v137, 0xffff0000, v24
	v_pk_fma_f32 v[112:113], v[10:11], v[58:59], v[112:113]
	v_pk_fma_f32 v[134:135], v[16:17], v[136:137], v[134:135]
	v_pk_fma_f32 v[112:113], v[14:15], v[50:51], v[112:113]
	v_cndmask_b32_e64 v25, v101, 0, vcc
	v_pk_fma_f32 v[116:117], v[18:19], v[40:41], v[112:113]
	v_pk_fma_f32 v[112:113], v[16:17], v[38:39], v[114:115]
	v_lshlrev_b32_e32 v138, 16, v25
	v_pk_mul_f32 v[114:115], v[112:113], v[222:223] op_sel_hi:[1,0]
	v_exp_f32_e32 v114, v114
	v_exp_f32_e32 v115, v115
	v_and_b32_e32 v139, 0xffff0000, v25
	v_pk_fma_f32 v[142:143], v[0:1], v[38:39], 0 op_sel_hi:[1,1,0]
	v_pk_add_f32 v[114:115], v[114:115], 1.0 op_sel_hi:[1,0]
	v_rcp_f32_e32 v114, v114
	v_rcp_f32_e32 v115, v115
	v_pk_fma_f32 v[142:143], v[4:5], v[30:31], v[142:143]
	s_waitcnt vmcnt(2)
	v_cndmask_b32_e64 v26, v102, 0, vcc
	v_pk_fma_f32 v[142:143], v[8:9], v[20:21], v[142:143]
	v_pk_mul_f32 v[112:113], v[112:113], v[114:115]
	v_pk_mul_f32 v[114:115], v[116:117], v[222:223] op_sel_hi:[1,0]
	v_exp_f32_e32 v114, v114
	v_exp_f32_e32 v115, v115
	v_pk_fma_f32 v[136:137], v[12:13], v[136:137], v[142:143]
	v_cndmask_b32_e64 v27, v103, 0, vcc
	v_pk_add_f32 v[114:115], v[114:115], 1.0 op_sel_hi:[1,0]
	v_rcp_f32_e32 v114, v114
	v_rcp_f32_e32 v115, v115
	v_lshlrev_b32_e32 v142, 16, v27
	v_and_b32_e32 v143, 0xffff0000, v27
	s_movk_i32 s8, 0x880
	v_pk_mul_f32 v[114:115], v[116:117], v[114:115]
	v_pk_fma_f32 v[116:117], v[2:3], v[54:55], 0 op_sel_hi:[1,1,0]
	v_cvt_pk_bf16_f32 v28, v28, v29
	v_pk_fma_f32 v[116:117], v[6:7], v[58:59], v[116:117]
	v_cvt_pk_bf16_f32 v29, v34, v35
	v_pk_fma_f32 v[116:117], v[10:11], v[50:51], v[116:117]
	v_mul_lo_u32 v34, v122, s8
	v_pk_fma_f32 v[116:117], v[14:15], v[40:41], v[116:117]
	v_add3_u32 v122, 0, v132, v34
	v_pk_fma_f32 v[120:121], v[18:19], v[32:33], v[116:117]
	v_pk_fma_f32 v[116:117], v[16:17], v[30:31], v[118:119]
	v_cvt_pk_bf16_f32 v34, v60, v61
	v_pk_mul_f32 v[118:119], v[116:117], v[222:223] op_sel_hi:[1,0]
	v_exp_f32_e32 v118, v118
	v_exp_f32_e32 v119, v119
	v_cvt_pk_bf16_f32 v35, v62, v63
	v_add_u32_e32 v60, 0x8800, v122
	v_pk_add_f32 v[118:119], v[118:119], 1.0 op_sel_hi:[1,0]
	v_rcp_f32_e32 v118, v118
	v_rcp_f32_e32 v119, v119
	ds_write2_b64 v60, v[28:29], v[34:35] offset1:34
	v_cvt_pk_bf16_f32 v28, v108, v109
	v_cvt_pk_bf16_f32 v29, v110, v111
	v_pk_mul_f32 v[116:117], v[116:117], v[118:119]
	v_pk_mul_f32 v[118:119], v[120:121], v[222:223] op_sel_hi:[1,0]
	v_exp_f32_e32 v118, v118
	v_exp_f32_e32 v119, v119
	v_cvt_pk_bf16_f32 v34, v112, v113
	v_cvt_pk_bf16_f32 v35, v114, v115
	v_pk_add_f32 v[118:119], v[118:119], 1.0 op_sel_hi:[1,0]
	v_rcp_f32_e32 v118, v118
	v_rcp_f32_e32 v119, v119
	ds_write2_b64 v60, v[28:29], v[34:35] offset0:68 offset1:102
	v_cvt_pk_bf16_f32 v28, v116, v117
	s_mov_b64 s[8:9], 0
	v_pk_mul_f32 v[118:119], v[120:121], v[118:119]
	v_pk_fma_f32 v[120:121], v[2:3], v[58:59], 0 op_sel_hi:[1,1,0]
	v_cvt_pk_bf16_f32 v29, v118, v119
	v_pk_fma_f32 v[120:121], v[6:7], v[50:51], v[120:121]
	s_nop 0
	v_pk_fma_f32 v[120:121], v[10:11], v[40:41], v[120:121]
	s_nop 0
	v_pk_fma_f32 v[120:121], v[14:15], v[32:33], v[120:121]
	s_nop 0
	v_pk_fma_f32 v[126:127], v[18:19], v[22:23], v[120:121]
	v_pk_fma_f32 v[120:121], v[16:17], v[20:21], v[124:125]
	s_nop 0
	v_mul_f32_e32 v123, 0xbfb8aa3b, v120
	v_exp_f32_e32 v123, v123
	s_nop 0
	v_add_f32_e32 v123, 1.0, v123
	v_rcp_f32_e32 v124, v123
	v_mul_f32_e32 v123, 0xbfb8aa3b, v121
	v_exp_f32_e32 v123, v123
	s_nop 0
	v_add_f32_e32 v123, 1.0, v123
	v_rcp_f32_e32 v125, v123
	v_mul_f32_e32 v123, 0xbfb8aa3b, v126
	v_exp_f32_e32 v123, v123
	v_pk_mul_f32 v[120:121], v[120:121], v[124:125]
	s_nop 0
	v_cvt_pk_bf16_f32 v34, v120, v121
	v_add_f32_e32 v123, 1.0, v123
	v_rcp_f32_e32 v124, v123
	v_mul_f32_e32 v123, 0xbfb8aa3b, v127
	v_exp_f32_e32 v123, v123
	s_nop 0
	v_add_f32_e32 v123, 1.0, v123
	v_rcp_f32_e32 v125, v123
	v_mul_f32_e32 v123, 0xbfb8aa3b, v134
	v_exp_f32_e32 v123, v123
	v_pk_mul_f32 v[124:125], v[126:127], v[124:125]
	v_pk_fma_f32 v[126:127], v[2:3], v[50:51], 0 op_sel_hi:[1,1,0]
	v_add_f32_e32 v123, 1.0, v123
	v_rcp_f32_e32 v140, v123
	v_mul_f32_e32 v123, 0xbfb8aa3b, v135
	v_exp_f32_e32 v123, v123
	v_pk_fma_f32 v[126:127], v[6:7], v[40:41], v[126:127]
	v_cvt_pk_bf16_f32 v35, v124, v125
	v_pk_fma_f32 v[126:127], v[10:11], v[32:33], v[126:127]
	v_add_f32_e32 v123, 1.0, v123
	v_pk_fma_f32 v[126:127], v[14:15], v[22:23], v[126:127]
	v_rcp_f32_e32 v141, v123
	v_pk_fma_f32 v[126:127], v[18:19], v[138:139], v[126:127]
	ds_write2_b64 v60, v[28:29], v[34:35] offset0:136 offset1:170
	v_mul_f32_e32 v123, 0xbfb8aa3b, v126
	v_exp_f32_e32 v123, v123
	v_pk_mul_f32 v[134:135], v[134:135], v[140:141]
	v_add_f32_e32 v123, 1.0, v123
	v_rcp_f32_e32 v140, v123
	v_mul_f32_e32 v123, 0xbfb8aa3b, v127
	v_exp_f32_e32 v123, v123
	v_cvt_pk_bf16_f32 v28, v134, v135
	v_add_f32_e32 v123, 1.0, v123
	v_rcp_f32_e32 v141, v123
	s_nop 0
	v_pk_mul_f32 v[126:127], v[126:127], v[140:141]
	v_pk_fma_f32 v[140:141], v[2:3], v[40:41], 0 op_sel_hi:[1,1,0]
	v_cvt_pk_bf16_f32 v29, v126, v127
	v_pk_fma_f32 v[140:141], v[6:7], v[32:33], v[140:141]
	s_nop 0
	v_pk_fma_f32 v[140:141], v[10:11], v[22:23], v[140:141]
	s_nop 0
	v_pk_fma_f32 v[138:139], v[14:15], v[138:139], v[140:141]
	v_lshlrev_b32_e32 v140, 16, v26
	v_and_b32_e32 v141, 0xffff0000, v26
	v_pk_fma_f32 v[136:137], v[16:17], v[140:141], v[136:137]
	v_pk_fma_f32 v[138:139], v[18:19], v[142:143], v[138:139]
	v_mul_f32_e32 v123, 0xbfb8aa3b, v136
	v_exp_f32_e32 v123, v123
	s_nop 0
	v_add_f32_e32 v123, 1.0, v123
	v_rcp_f32_e32 v140, v123
	v_mul_f32_e32 v123, 0xbfb8aa3b, v137
	v_exp_f32_e32 v123, v123
	s_nop 0
	v_add_f32_e32 v123, 1.0, v123
	v_rcp_f32_e32 v141, v123
	v_mul_f32_e32 v123, 0xbfb8aa3b, v138
	v_exp_f32_e32 v123, v123
	v_pk_mul_f32 v[136:137], v[136:137], v[140:141]
	s_nop 0
	v_cvt_pk_bf16_f32 v34, v136, v137
	v_add_f32_e32 v123, 1.0, v123
	v_rcp_f32_e32 v140, v123
	v_mul_f32_e32 v123, 0xbfb8aa3b, v139
	v_exp_f32_e32 v123, v123
	s_nop 0
	v_add_f32_e32 v123, 1.0, v123
	v_rcp_f32_e32 v141, v123
	s_nop 0
	v_pk_mul_f32 v[138:139], v[138:139], v[140:141]
	s_nop 0
	v_cvt_pk_bf16_f32 v35, v138, v139
	ds_write2_b64 v60, v[28:29], v[34:35] offset0:204 offset1:238
.LBB0_400:
	s_andn2_b64 vcc, exec, s[8:9]
	s_cbranch_vccnz .LBB0_402
	s_add_i32 s8, s45, s13
	s_add_i32 s9, s8, 0xffffff00
	s_cmp_lt_i32 s88, 4
	s_cselect_b32 s8, s8, s9
	s_movk_i32 s9, 0xf0
	s_cselect_b32 s13, s9, 0x7f0
	s_add_i32 s14, s8, s25
	s_cmp_eq_u32 s14, 0
	s_cselect_b64 s[8:9], -1, 0
	v_cndmask_b32_e64 v64, v106, 0, s[8:9]
	v_cndmask_b32_e64 v66, v104, 0, s[8:9]
	v_lshlrev_b32_e32 v24, 16, v64
	v_and_b32_e32 v25, 0xffff0000, v64
	v_pk_fma_f32 v[24:25], v[0:1], v[24:25], 0 op_sel_hi:[1,1,0]
	v_lshlrev_b32_e32 v28, 16, v66
	v_and_b32_e32 v29, 0xffff0000, v66
	v_pk_fma_f32 v[24:25], v[4:5], v[28:29], v[24:25]
	v_cndmask_b32_e64 v65, v107, 0, s[8:9]
	v_pk_fma_f32 v[24:25], v[8:9], v[36:37], v[24:25]
	v_cndmask_b32_e64 v67, v105, 0, s[8:9]
	v_pk_fma_f32 v[24:25], v[12:13], v[44:45], v[24:25]
	v_lshlrev_b32_e32 v26, 16, v65
	v_pk_fma_f32 v[24:25], v[16:17], v[52:53], v[24:25]
	v_and_b32_e32 v27, 0xffff0000, v65
	v_pk_mul_f32 v[60:61], v[24:25], v[222:223] op_sel_hi:[1,0]
	v_exp_f32_e32 v60, v60
	v_exp_f32_e32 v61, v61
	v_pk_fma_f32 v[26:27], v[2:3], v[26:27], 0 op_sel_hi:[1,1,0]
	v_lshlrev_b32_e32 v34, 16, v67
	v_and_b32_e32 v35, 0xffff0000, v67
	v_pk_add_f32 v[60:61], v[60:61], 1.0 op_sel_hi:[1,0]
	v_pk_fma_f32 v[26:27], v[6:7], v[34:35], v[26:27]
	v_rcp_f32_e32 v60, v60
	v_rcp_f32_e32 v61, v61
	v_pk_fma_f32 v[26:27], v[10:11], v[42:43], v[26:27]
	v_pk_fma_f32 v[28:29], v[0:1], v[28:29], 0 op_sel_hi:[1,1,0]
	v_pk_fma_f32 v[26:27], v[14:15], v[46:47], v[26:27]
	v_pk_mul_f32 v[24:25], v[24:25], v[60:61]
	v_pk_fma_f32 v[26:27], v[18:19], v[54:55], v[26:27]
	v_pk_fma_f32 v[28:29], v[4:5], v[36:37], v[28:29]
	v_pk_mul_f32 v[60:61], v[26:27], v[222:223] op_sel_hi:[1,0]
	v_exp_f32_e32 v60, v60
	v_exp_f32_e32 v61, v61
	v_mov_b32_e32 v62, v25
	v_pk_fma_f32 v[28:29], v[8:9], v[44:45], v[28:29]
	v_pk_add_f32 v[60:61], v[60:61], 1.0 op_sel_hi:[1,0]
	v_rcp_f32_e32 v60, v60
	v_rcp_f32_e32 v61, v61
	v_pk_fma_f32 v[28:29], v[12:13], v[52:53], v[28:29]
	v_pk_fma_f32 v[34:35], v[2:3], v[34:35], 0 op_sel_hi:[1,1,0]
	v_pk_fma_f32 v[28:29], v[16:17], v[56:57], v[28:29]
	v_pk_mul_f32 v[26:27], v[26:27], v[60:61]
	v_mov_b32_e32 v60, v24
	v_mov_b32_e32 v63, v27
	v_mov_b32_e32 v61, v26
	v_pk_mul_f32 v[62:63], v[62:63], v[62:63]
	v_pk_fma_f32 v[34:35], v[6:7], v[42:43], v[34:35]
	v_pk_fma_f32 v[60:61], v[60:61], v[60:61], v[62:63]
	v_pk_fma_f32 v[34:35], v[10:11], v[46:47], v[34:35]
	v_add_f32_e32 v134, v60, v61
	v_pk_mul_f32 v[60:61], v[28:29], v[222:223] op_sel_hi:[1,0]
	v_exp_f32_e32 v60, v60
	v_exp_f32_e32 v61, v61
	v_pk_fma_f32 v[34:35], v[14:15], v[54:55], v[34:35]
	v_pk_fma_f32 v[36:37], v[0:1], v[36:37], 0 op_sel_hi:[1,1,0]
	v_pk_add_f32 v[60:61], v[60:61], 1.0 op_sel_hi:[1,0]
	v_rcp_f32_e32 v60, v60
	v_rcp_f32_e32 v61, v61
	v_pk_fma_f32 v[34:35], v[18:19], v[58:59], v[34:35]
	v_pk_fma_f32 v[36:37], v[4:5], v[44:45], v[36:37]
	v_pk_fma_f32 v[42:43], v[2:3], v[42:43], 0 op_sel_hi:[1,1,0]
	v_pk_mul_f32 v[28:29], v[28:29], v[60:61]
	v_pk_mul_f32 v[60:61], v[34:35], v[222:223] op_sel_hi:[1,0]
	v_exp_f32_e32 v60, v60
	v_exp_f32_e32 v61, v61
	v_mov_b32_e32 v62, v29
	v_pk_fma_f32 v[36:37], v[8:9], v[52:53], v[36:37]
	v_pk_add_f32 v[60:61], v[60:61], 1.0 op_sel_hi:[1,0]
	v_rcp_f32_e32 v60, v60
	v_rcp_f32_e32 v61, v61
	v_pk_fma_f32 v[36:37], v[12:13], v[56:57], v[36:37]
	v_pk_fma_f32 v[42:43], v[6:7], v[46:47], v[42:43]
	v_pk_fma_f32 v[36:37], v[16:17], v[48:49], v[36:37]
	v_pk_mul_f32 v[34:35], v[34:35], v[60:61]
	v_mov_b32_e32 v60, v28
	v_mov_b32_e32 v63, v35
	v_mov_b32_e32 v61, v34
	v_pk_mul_f32 v[62:63], v[62:63], v[62:63]
	v_pk_fma_f32 v[42:43], v[10:11], v[54:55], v[42:43]
	v_pk_fma_f32 v[60:61], v[60:61], v[60:61], v[62:63]
	v_pk_fma_f32 v[42:43], v[14:15], v[58:59], v[42:43]
	v_add_f32_e32 v135, v60, v61
	v_pk_mul_f32 v[60:61], v[36:37], v[222:223] op_sel_hi:[1,0]
	v_exp_f32_e32 v60, v60
	v_exp_f32_e32 v61, v61
	v_pk_fma_f32 v[42:43], v[18:19], v[50:51], v[42:43]
	v_pk_fma_f32 v[44:45], v[0:1], v[44:45], 0 op_sel_hi:[1,1,0]
	v_pk_add_f32 v[60:61], v[60:61], 1.0 op_sel_hi:[1,0]
	v_rcp_f32_e32 v60, v60
	v_rcp_f32_e32 v61, v61
	v_pk_fma_f32 v[44:45], v[4:5], v[52:53], v[44:45]
	v_pk_fma_f32 v[46:47], v[2:3], v[46:47], 0 op_sel_hi:[1,1,0]
	v_pk_fma_f32 v[44:45], v[8:9], v[56:57], v[44:45]
	v_pk_mul_f32 v[36:37], v[36:37], v[60:61]
	v_pk_mul_f32 v[60:61], v[42:43], v[222:223] op_sel_hi:[1,0]
	v_exp_f32_e32 v60, v60
	v_exp_f32_e32 v61, v61
	v_mov_b32_e32 v62, v37
	v_pk_fma_f32 v[44:45], v[12:13], v[48:49], v[44:45]
	v_pk_add_f32 v[60:61], v[60:61], 1.0 op_sel_hi:[1,0]
	v_rcp_f32_e32 v60, v60
	v_rcp_f32_e32 v61, v61
	v_pk_fma_f32 v[44:45], v[16:17], v[38:39], v[44:45]
	v_pk_fma_f32 v[46:47], v[6:7], v[54:55], v[46:47]
	v_pk_fma_f32 v[52:53], v[0:1], v[52:53], 0 op_sel_hi:[1,1,0]
	v_pk_mul_f32 v[42:43], v[42:43], v[60:61]
	v_mov_b32_e32 v60, v36
	v_mov_b32_e32 v63, v43
	v_mov_b32_e32 v61, v42
	v_pk_mul_f32 v[62:63], v[62:63], v[62:63]
	v_pk_fma_f32 v[46:47], v[10:11], v[58:59], v[46:47]
	v_pk_fma_f32 v[60:61], v[60:61], v[60:61], v[62:63]
	v_pk_fma_f32 v[46:47], v[14:15], v[50:51], v[46:47]
	v_add_f32_e32 v136, v60, v61
	v_pk_mul_f32 v[60:61], v[44:45], v[222:223] op_sel_hi:[1,0]
	v_exp_f32_e32 v60, v60
	v_exp_f32_e32 v61, v61
	v_pk_fma_f32 v[46:47], v[18:19], v[40:41], v[46:47]
	v_pk_fma_f32 v[52:53], v[4:5], v[56:57], v[52:53]
	v_pk_add_f32 v[60:61], v[60:61], 1.0 op_sel_hi:[1,0]
	v_rcp_f32_e32 v60, v60
	v_rcp_f32_e32 v61, v61
	v_pk_fma_f32 v[52:53], v[8:9], v[48:49], v[52:53]
	v_pk_fma_f32 v[54:55], v[2:3], v[54:55], 0 op_sel_hi:[1,1,0]
	v_pk_fma_f32 v[52:53], v[12:13], v[38:39], v[52:53]
	v_pk_mul_f32 v[44:45], v[44:45], v[60:61]
	v_pk_mul_f32 v[60:61], v[46:47], v[222:223] op_sel_hi:[1,0]
	v_exp_f32_e32 v60, v60
	v_exp_f32_e32 v61, v61
	v_mov_b32_e32 v62, v45
	v_pk_fma_f32 v[52:53], v[16:17], v[30:31], v[52:53]
	v_pk_add_f32 v[60:61], v[60:61], 1.0 op_sel_hi:[1,0]
	v_rcp_f32_e32 v60, v60
	v_rcp_f32_e32 v61, v61
	v_pk_fma_f32 v[54:55], v[6:7], v[58:59], v[54:55]
	v_pk_fma_f32 v[56:57], v[0:1], v[56:57], 0 op_sel_hi:[1,1,0]
	v_pk_fma_f32 v[54:55], v[10:11], v[50:51], v[54:55]
	v_pk_mul_f32 v[46:47], v[46:47], v[60:61]
	v_mov_b32_e32 v60, v44
	v_mov_b32_e32 v63, v47
	v_mov_b32_e32 v61, v46
	v_pk_mul_f32 v[62:63], v[62:63], v[62:63]
	v_pk_fma_f32 v[54:55], v[14:15], v[40:41], v[54:55]
	v_pk_fma_f32 v[60:61], v[60:61], v[60:61], v[62:63]
	v_pk_fma_f32 v[54:55], v[18:19], v[32:33], v[54:55]
	v_add_f32_e32 v137, v60, v61
	v_pk_mul_f32 v[60:61], v[52:53], v[222:223] op_sel_hi:[1,0]
	v_exp_f32_e32 v60, v60
	v_exp_f32_e32 v61, v61
	v_pk_fma_f32 v[56:57], v[4:5], v[48:49], v[56:57]
	v_pk_fma_f32 v[58:59], v[2:3], v[58:59], 0 op_sel_hi:[1,1,0]
	v_pk_add_f32 v[60:61], v[60:61], 1.0 op_sel_hi:[1,0]
	v_rcp_f32_e32 v60, v60
	v_rcp_f32_e32 v61, v61
	v_pk_fma_f32 v[56:57], v[8:9], v[38:39], v[56:57]
	v_pk_fma_f32 v[58:59], v[6:7], v[50:51], v[58:59]
	v_pk_fma_f32 v[56:57], v[12:13], v[30:31], v[56:57]
	v_pk_mul_f32 v[52:53], v[52:53], v[60:61]
	v_pk_mul_f32 v[60:61], v[54:55], v[222:223] op_sel_hi:[1,0]
	v_exp_f32_e32 v60, v60
	v_exp_f32_e32 v61, v61
	v_mov_b32_e32 v62, v53
	v_pk_fma_f32 v[56:57], v[16:17], v[20:21], v[56:57]
	v_pk_add_f32 v[60:61], v[60:61], 1.0 op_sel_hi:[1,0]
	v_rcp_f32_e32 v60, v60
	v_rcp_f32_e32 v61, v61
	v_pk_fma_f32 v[58:59], v[10:11], v[40:41], v[58:59]
	v_pk_fma_f32 v[48:49], v[0:1], v[48:49], 0 op_sel_hi:[1,1,0]
	v_pk_fma_f32 v[58:59], v[14:15], v[32:33], v[58:59]
	v_pk_mul_f32 v[54:55], v[54:55], v[60:61]
	v_mov_b32_e32 v60, v52
	v_mov_b32_e32 v63, v55
	v_mov_b32_e32 v61, v54
	v_pk_mul_f32 v[62:63], v[62:63], v[62:63]
	v_pk_fma_f32 v[58:59], v[18:19], v[22:23], v[58:59]
	v_pk_fma_f32 v[60:61], v[60:61], v[60:61], v[62:63]
	v_pk_fma_f32 v[48:49], v[4:5], v[38:39], v[48:49]
	v_add_f32_e32 v138, v60, v61
	v_pk_mul_f32 v[60:61], v[56:57], v[222:223] op_sel_hi:[1,0]
	v_exp_f32_e32 v60, v60
	v_exp_f32_e32 v61, v61
	v_pk_fma_f32 v[48:49], v[8:9], v[30:31], v[48:49]
	v_pk_fma_f32 v[50:51], v[2:3], v[50:51], 0 op_sel_hi:[1,1,0]
	v_pk_add_f32 v[60:61], v[60:61], 1.0 op_sel_hi:[1,0]
	v_rcp_f32_e32 v60, v60
	v_rcp_f32_e32 v61, v61
	v_pk_fma_f32 v[48:49], v[12:13], v[20:21], v[48:49]
	v_pk_fma_f32 v[50:51], v[6:7], v[40:41], v[50:51]
	v_pk_fma_f32 v[38:39], v[0:1], v[38:39], 0 op_sel_hi:[1,1,0]
	v_pk_mul_f32 v[56:57], v[56:57], v[60:61]
	v_pk_mul_f32 v[60:61], v[58:59], v[222:223] op_sel_hi:[1,0]
	v_exp_f32_e32 v60, v60
	v_exp_f32_e32 v61, v61
	v_mov_b32_e32 v62, v57
	v_pk_fma_f32 v[50:51], v[10:11], v[32:33], v[50:51]
	v_pk_add_f32 v[60:61], v[60:61], 1.0 op_sel_hi:[1,0]
	v_rcp_f32_e32 v60, v60
	v_rcp_f32_e32 v61, v61
	v_pk_fma_f32 v[50:51], v[14:15], v[22:23], v[50:51]
	v_pk_fma_f32 v[38:39], v[4:5], v[30:31], v[38:39]
	v_pk_fma_f32 v[40:41], v[2:3], v[40:41], 0 op_sel_hi:[1,1,0]
	v_pk_mul_f32 v[58:59], v[58:59], v[60:61]
	v_mov_b32_e32 v60, v56
	v_mov_b32_e32 v63, v59
	v_mov_b32_e32 v61, v58
	v_pk_mul_f32 v[62:63], v[62:63], v[62:63]
	v_pk_fma_f32 v[38:39], v[8:9], v[20:21], v[38:39]
	v_pk_fma_f32 v[60:61], v[60:61], v[60:61], v[62:63]
	s_waitcnt vmcnt(3)
	v_lshlrev_b32_e32 v62, 16, v101
	v_add_f32_e32 v139, v60, v61
	v_lshlrev_b32_e32 v60, 16, v100
	v_and_b32_e32 v61, 0xffff0000, v100
	v_pk_fma_f32 v[48:49], v[16:17], v[60:61], v[48:49]
	v_and_b32_e32 v63, 0xffff0000, v101
	v_pk_mul_f32 v[104:105], v[48:49], v[222:223] op_sel_hi:[1,0]
	v_exp_f32_e32 v104, v104
	v_exp_f32_e32 v105, v105
	v_pk_fma_f32 v[50:51], v[18:19], v[62:63], v[50:51]
	v_pk_fma_f32 v[38:39], v[12:13], v[60:61], v[38:39]
	v_pk_add_f32 v[104:105], v[104:105], 1.0 op_sel_hi:[1,0]
	v_rcp_f32_e32 v104, v104
	v_rcp_f32_e32 v105, v105
	v_pk_fma_f32 v[40:41], v[6:7], v[32:33], v[40:41]
	v_pk_fma_f32 v[30:31], v[0:1], v[30:31], 0 op_sel_hi:[1,1,0]
	v_pk_fma_f32 v[40:41], v[10:11], v[22:23], v[40:41]
	v_pk_mul_f32 v[48:49], v[48:49], v[104:105]
	v_pk_mul_f32 v[104:105], v[50:51], v[222:223] op_sel_hi:[1,0]
	v_exp_f32_e32 v104, v104
	v_exp_f32_e32 v105, v105
	v_mov_b32_e32 v106, v49
	v_pk_fma_f32 v[40:41], v[14:15], v[62:63], v[40:41]
	v_pk_add_f32 v[104:105], v[104:105], 1.0 op_sel_hi:[1,0]
	v_rcp_f32_e32 v104, v104
	v_rcp_f32_e32 v105, v105
	v_pk_fma_f32 v[30:31], v[4:5], v[20:21], v[30:31]
	v_pk_fma_f32 v[32:33], v[2:3], v[32:33], 0 op_sel_hi:[1,1,0]
	v_pk_fma_f32 v[30:31], v[8:9], v[60:61], v[30:31]
	v_pk_mul_f32 v[50:51], v[50:51], v[104:105]
	v_mov_b32_e32 v104, v48
	v_mov_b32_e32 v107, v51
	v_mov_b32_e32 v105, v50
	v_pk_mul_f32 v[106:107], v[106:107], v[106:107]
	v_pk_fma_f32 v[32:33], v[6:7], v[22:23], v[32:33]
	v_pk_fma_f32 v[104:105], v[104:105], v[104:105], v[106:107]
	s_waitcnt vmcnt(2)
	v_lshlrev_b32_e32 v106, 16, v103
	v_add_f32_e32 v140, v104, v105
	v_lshlrev_b32_e32 v104, 16, v102
	v_and_b32_e32 v105, 0xffff0000, v102
	v_pk_fma_f32 v[38:39], v[16:17], v[104:105], v[38:39]
	v_and_b32_e32 v107, 0xffff0000, v103
	v_pk_mul_f32 v[108:109], v[38:39], v[222:223] op_sel_hi:[1,0]
	v_exp_f32_e32 v108, v108
	v_exp_f32_e32 v109, v109
	v_pk_fma_f32 v[40:41], v[18:19], v[106:107], v[40:41]
	v_pk_fma_f32 v[30:31], v[12:13], v[104:105], v[30:31]
	v_pk_add_f32 v[108:109], v[108:109], 1.0 op_sel_hi:[1,0]
	v_rcp_f32_e32 v108, v108
	v_rcp_f32_e32 v109, v109
	v_pk_fma_f32 v[32:33], v[10:11], v[62:63], v[32:33]
	v_pk_fma_f32 v[20:21], v[0:1], v[20:21], 0 op_sel_hi:[1,1,0]
	v_pk_fma_f32 v[32:33], v[14:15], v[106:107], v[32:33]
	v_pk_mul_f32 v[38:39], v[38:39], v[108:109]
	v_pk_mul_f32 v[108:109], v[40:41], v[222:223] op_sel_hi:[1,0]
	v_exp_f32_e32 v108, v108
	v_exp_f32_e32 v109, v109
	v_mov_b32_e32 v110, v39
	v_pk_fma_f32 v[20:21], v[4:5], v[60:61], v[20:21]
	v_pk_add_f32 v[108:109], v[108:109], 1.0 op_sel_hi:[1,0]
	v_rcp_f32_e32 v108, v108
	v_rcp_f32_e32 v109, v109
	v_pk_fma_f32 v[20:21], v[8:9], v[104:105], v[20:21]
	v_pk_fma_f32 v[22:23], v[2:3], v[22:23], 0 op_sel_hi:[1,1,0]
	v_pk_fma_f32 v[60:61], v[0:1], v[60:61], 0 op_sel_hi:[1,1,0]
	v_pk_mul_f32 v[40:41], v[40:41], v[108:109]
	v_mov_b32_e32 v108, v38
	v_mov_b32_e32 v111, v41
	v_mov_b32_e32 v109, v40
	v_pk_mul_f32 v[110:111], v[110:111], v[110:111]
	v_pk_fma_f32 v[22:23], v[6:7], v[62:63], v[22:23]
	v_pk_fma_f32 v[108:109], v[108:109], v[108:109], v[110:111]
	v_lshlrev_b32_e32 v110, 16, v69
	v_add_f32_e32 v141, v108, v109
	v_lshlrev_b32_e32 v108, 16, v68
	v_and_b32_e32 v109, 0xffff0000, v68
	v_pk_fma_f32 v[30:31], v[16:17], v[108:109], v[30:31]
	v_and_b32_e32 v111, 0xffff0000, v69
	v_pk_mul_f32 v[112:113], v[30:31], v[222:223] op_sel_hi:[1,0]
	v_exp_f32_e32 v112, v112
	v_exp_f32_e32 v113, v113
	v_pk_fma_f32 v[32:33], v[18:19], v[110:111], v[32:33]
	v_pk_fma_f32 v[20:21], v[12:13], v[108:109], v[20:21]
	v_pk_add_f32 v[112:113], v[112:113], 1.0 op_sel_hi:[1,0]
	v_rcp_f32_e32 v112, v112
	v_rcp_f32_e32 v113, v113
	v_pk_fma_f32 v[22:23], v[10:11], v[106:107], v[22:23]
	v_pk_fma_f32 v[60:61], v[4:5], v[104:105], v[60:61]
	v_pk_fma_f32 v[22:23], v[14:15], v[110:111], v[22:23]
	v_pk_mul_f32 v[30:31], v[30:31], v[112:113]
	v_pk_mul_f32 v[112:113], v[32:33], v[222:223] op_sel_hi:[1,0]
	v_exp_f32_e32 v112, v112
	v_exp_f32_e32 v113, v113
	v_mov_b32_e32 v114, v31
	v_pk_fma_f32 v[60:61], v[8:9], v[108:109], v[60:61]
	v_pk_add_f32 v[112:113], v[112:113], 1.0 op_sel_hi:[1,0]
	v_rcp_f32_e32 v112, v112
	v_rcp_f32_e32 v113, v113
	v_pk_fma_f32 v[62:63], v[2:3], v[62:63], 0 op_sel_hi:[1,1,0]
	v_pk_fma_f32 v[104:105], v[0:1], v[104:105], 0 op_sel_hi:[1,1,0]
	v_pk_fma_f32 v[62:63], v[6:7], v[106:107], v[62:63]
	v_pk_mul_f32 v[32:33], v[32:33], v[112:113]
	v_mov_b32_e32 v112, v30
	v_mov_b32_e32 v115, v33
	v_mov_b32_e32 v113, v32
	v_pk_mul_f32 v[114:115], v[114:115], v[114:115]
	v_pk_fma_f32 v[62:63], v[10:11], v[110:111], v[62:63]
	v_pk_fma_f32 v[112:113], v[112:113], v[112:113], v[114:115]
	v_lshlrev_b32_e32 v114, 16, v71
	v_add_f32_e32 v142, v112, v113
	v_lshlrev_b32_e32 v112, 16, v70
	v_and_b32_e32 v113, 0xffff0000, v70
	v_pk_fma_f32 v[20:21], v[16:17], v[112:113], v[20:21]
	v_and_b32_e32 v115, 0xffff0000, v71
	v_pk_mul_f32 v[116:117], v[20:21], v[222:223] op_sel_hi:[1,0]
	v_exp_f32_e32 v116, v116
	v_exp_f32_e32 v117, v117
	v_pk_fma_f32 v[22:23], v[18:19], v[114:115], v[22:23]
	v_pk_fma_f32 v[60:61], v[12:13], v[112:113], v[60:61]
	v_pk_add_f32 v[116:117], v[116:117], 1.0 op_sel_hi:[1,0]
	v_rcp_f32_e32 v116, v116
	v_rcp_f32_e32 v117, v117
	v_pk_fma_f32 v[62:63], v[14:15], v[114:115], v[62:63]
	v_pk_fma_f32 v[104:105], v[4:5], v[108:109], v[104:105]
	v_pk_fma_f32 v[106:107], v[2:3], v[106:107], 0 op_sel_hi:[1,1,0]
	v_pk_mul_f32 v[20:21], v[20:21], v[116:117]
	v_pk_mul_f32 v[116:117], v[22:23], v[222:223] op_sel_hi:[1,0]
	v_exp_f32_e32 v116, v116
	v_exp_f32_e32 v117, v117
	v_mov_b32_e32 v118, v21
	v_pk_fma_f32 v[104:105], v[8:9], v[112:113], v[104:105]
	v_pk_add_f32 v[116:117], v[116:117], 1.0 op_sel_hi:[1,0]
	v_rcp_f32_e32 v116, v116
	v_rcp_f32_e32 v117, v117
	v_pk_fma_f32 v[106:107], v[6:7], v[110:111], v[106:107]
	v_pk_fma_f32 v[108:109], v[0:1], v[108:109], 0 op_sel_hi:[1,1,0]
	v_pk_fma_f32 v[106:107], v[10:11], v[114:115], v[106:107]
	v_pk_mul_f32 v[22:23], v[22:23], v[116:117]
	v_mov_b32_e32 v116, v20
	v_mov_b32_e32 v119, v23
	v_mov_b32_e32 v117, v22
	v_pk_mul_f32 v[118:119], v[118:119], v[118:119]
	v_pk_fma_f32 v[108:109], v[4:5], v[112:113], v[108:109]
	v_pk_fma_f32 v[116:117], v[116:117], v[116:117], v[118:119]
	v_lshlrev_b32_e32 v118, 16, v77
	v_add_f32_e32 v143, v116, v117
	v_lshlrev_b32_e32 v116, 16, v76
	v_and_b32_e32 v117, 0xffff0000, v76
	v_pk_fma_f32 v[60:61], v[16:17], v[116:117], v[60:61]
	v_and_b32_e32 v119, 0xffff0000, v77
	v_pk_mul_f32 v[120:121], v[60:61], v[222:223] op_sel_hi:[1,0]
	v_exp_f32_e32 v120, v120
	v_exp_f32_e32 v121, v121
	v_pk_fma_f32 v[62:63], v[18:19], v[118:119], v[62:63]
	v_pk_fma_f32 v[104:105], v[12:13], v[116:117], v[104:105]
	v_pk_add_f32 v[120:121], v[120:121], 1.0 op_sel_hi:[1,0]
	v_rcp_f32_e32 v120, v120
	v_rcp_f32_e32 v121, v121
	v_pk_fma_f32 v[106:107], v[14:15], v[118:119], v[106:107]
	v_pk_fma_f32 v[108:109], v[8:9], v[116:117], v[108:109]
	v_pk_fma_f32 v[110:111], v[2:3], v[110:111], 0 op_sel_hi:[1,1,0]
	v_pk_mul_f32 v[60:61], v[60:61], v[120:121]
	v_pk_mul_f32 v[120:121], v[62:63], v[222:223] op_sel_hi:[1,0]
	v_exp_f32_e32 v120, v120
	v_exp_f32_e32 v121, v121
	v_mov_b32_e32 v122, v61
	v_pk_fma_f32 v[110:111], v[6:7], v[114:115], v[110:111]
	v_pk_add_f32 v[120:121], v[120:121], 1.0 op_sel_hi:[1,0]
	v_rcp_f32_e32 v120, v120
	v_rcp_f32_e32 v121, v121
	v_pk_fma_f32 v[110:111], v[10:11], v[118:119], v[110:111]
	v_pk_fma_f32 v[112:113], v[0:1], v[112:113], 0 op_sel_hi:[1,1,0]
	v_pk_fma_f32 v[114:115], v[2:3], v[114:115], 0 op_sel_hi:[1,1,0]
	v_pk_mul_f32 v[62:63], v[62:63], v[120:121]
	v_mov_b32_e32 v120, v60
	v_mov_b32_e32 v123, v63
	v_mov_b32_e32 v121, v62
	v_pk_mul_f32 v[122:123], v[122:123], v[122:123]
	v_pk_fma_f32 v[112:113], v[4:5], v[116:117], v[112:113]
	v_pk_fma_f32 v[120:121], v[120:121], v[120:121], v[122:123]
	v_lshlrev_b32_e32 v122, 16, v79
	v_add_f32_e32 v144, v120, v121
	v_lshlrev_b32_e32 v120, 16, v78
	v_and_b32_e32 v121, 0xffff0000, v78
	v_pk_fma_f32 v[104:105], v[16:17], v[120:121], v[104:105]
	v_and_b32_e32 v123, 0xffff0000, v79
	v_pk_mul_f32 v[124:125], v[104:105], v[222:223] op_sel_hi:[1,0]
	v_exp_f32_e32 v124, v124
	v_exp_f32_e32 v125, v125
	v_pk_fma_f32 v[106:107], v[18:19], v[122:123], v[106:107]
	v_pk_fma_f32 v[108:109], v[12:13], v[120:121], v[108:109]
	v_pk_add_f32 v[124:125], v[124:125], 1.0 op_sel_hi:[1,0]
	v_rcp_f32_e32 v124, v124
	v_rcp_f32_e32 v125, v125
	v_pk_fma_f32 v[110:111], v[14:15], v[122:123], v[110:111]
	v_pk_fma_f32 v[112:113], v[8:9], v[120:121], v[112:113]
	v_pk_fma_f32 v[114:115], v[6:7], v[118:119], v[114:115]
	v_pk_mul_f32 v[104:105], v[104:105], v[124:125]
	v_pk_mul_f32 v[124:125], v[106:107], v[222:223] op_sel_hi:[1,0]
	v_exp_f32_e32 v124, v124
	v_exp_f32_e32 v125, v125
	v_mov_b32_e32 v126, v105
	v_pk_fma_f32 v[114:115], v[10:11], v[122:123], v[114:115]
	v_pk_add_f32 v[124:125], v[124:125], 1.0 op_sel_hi:[1,0]
	v_rcp_f32_e32 v124, v124
	v_rcp_f32_e32 v125, v125
	s_cmp_eq_u32 s14, s13
	v_pk_fma_f32 v[116:117], v[0:1], v[116:117], 0 op_sel_hi:[1,1,0]
	s_cselect_b64 s[8:9], -1, 0
	v_pk_mul_f32 v[106:107], v[106:107], v[124:125]
	v_mov_b32_e32 v124, v104
	v_mov_b32_e32 v127, v107
	v_mov_b32_e32 v125, v106
	v_pk_mul_f32 v[126:127], v[126:127], v[126:127]
	v_pk_fma_f32 v[116:117], v[4:5], v[120:121], v[116:117]
	v_pk_fma_f32 v[124:125], v[124:125], v[124:125], v[126:127]
	v_lshlrev_b32_e32 v126, 16, v81
	v_add_f32_e32 v145, v124, v125
	v_lshlrev_b32_e32 v124, 16, v80
	v_and_b32_e32 v125, 0xffff0000, v80
	v_pk_fma_f32 v[108:109], v[16:17], v[124:125], v[108:109]
	v_and_b32_e32 v127, 0xffff0000, v81
	v_pk_mul_f32 v[146:147], v[108:109], v[222:223] op_sel_hi:[1,0]
	v_exp_f32_e32 v146, v146
	v_exp_f32_e32 v147, v147
	v_pk_fma_f32 v[110:111], v[18:19], v[126:127], v[110:111]
	v_pk_fma_f32 v[112:113], v[12:13], v[124:125], v[112:113]
	v_pk_add_f32 v[146:147], v[146:147], 1.0 op_sel_hi:[1,0]
	v_rcp_f32_e32 v146, v146
	v_rcp_f32_e32 v147, v147
	v_pk_fma_f32 v[114:115], v[14:15], v[126:127], v[114:115]
	v_pk_fma_f32 v[120:121], v[0:1], v[120:121], 0 op_sel_hi:[1,1,0]
	v_cndmask_b32_e64 v92, v92, 0, s[8:9]
	v_pk_mul_f32 v[108:109], v[108:109], v[146:147]
	v_pk_mul_f32 v[146:147], v[110:111], v[222:223] op_sel_hi:[1,0]
	v_exp_f32_e32 v146, v146
	v_exp_f32_e32 v147, v147
	v_mov_b32_e32 v148, v109
	v_pk_fma_f32 v[120:121], v[4:5], v[124:125], v[120:121]
	v_pk_add_f32 v[146:147], v[146:147], 1.0 op_sel_hi:[1,0]
	v_rcp_f32_e32 v146, v146
	v_rcp_f32_e32 v147, v147
	v_cndmask_b32_e64 v94, v94, 0, s[8:9]
	v_pk_fma_f32 v[116:117], v[8:9], v[124:125], v[116:117]
	v_lshlrev_b32_e32 v124, 16, v94
	v_pk_mul_f32 v[110:111], v[110:111], v[146:147]
	v_mov_b32_e32 v146, v108
	v_mov_b32_e32 v149, v111
	v_mov_b32_e32 v147, v110
	v_pk_mul_f32 v[148:149], v[148:149], v[148:149]
	v_and_b32_e32 v125, 0xffff0000, v94
	v_pk_fma_f32 v[146:147], v[146:147], v[146:147], v[148:149]
	v_lshlrev_b32_e32 v148, 16, v83
	v_add_f32_e32 v158, v146, v147
	v_lshlrev_b32_e32 v146, 16, v82
	v_and_b32_e32 v147, 0xffff0000, v82
	v_pk_fma_f32 v[112:113], v[16:17], v[146:147], v[112:113]
	v_and_b32_e32 v149, 0xffff0000, v83
	v_pk_mul_f32 v[150:151], v[112:113], v[222:223] op_sel_hi:[1,0]
	v_exp_f32_e32 v150, v150
	v_exp_f32_e32 v151, v151
	v_pk_fma_f32 v[114:115], v[18:19], v[148:149], v[114:115]
	v_pk_fma_f32 v[120:121], v[8:9], v[146:147], v[120:121]
	v_pk_add_f32 v[150:151], v[150:151], 1.0 op_sel_hi:[1,0]
	v_rcp_f32_e32 v150, v150
	v_rcp_f32_e32 v151, v151
	v_pk_fma_f32 v[116:117], v[12:13], v[146:147], v[116:117]
	v_pk_fma_f32 v[118:119], v[2:3], v[118:119], 0 op_sel_hi:[1,1,0]
	v_cndmask_b32_e64 v93, v93, 0, s[8:9]
	v_pk_mul_f32 v[112:113], v[112:113], v[150:151]
	v_pk_mul_f32 v[150:151], v[114:115], v[222:223] op_sel_hi:[1,0]
	v_exp_f32_e32 v150, v150
	v_exp_f32_e32 v151, v151
	v_mov_b32_e32 v152, v113
	v_pk_fma_f32 v[118:119], v[6:7], v[122:123], v[118:119]
	v_pk_add_f32 v[150:151], v[150:151], 1.0 op_sel_hi:[1,0]
	v_rcp_f32_e32 v150, v150
	v_rcp_f32_e32 v151, v151
	v_pk_fma_f32 v[122:123], v[2:3], v[122:123], 0 op_sel_hi:[1,1,0]
	v_cndmask_b32_e64 v95, v95, 0, s[8:9]
	v_pk_fma_f32 v[122:123], v[6:7], v[126:127], v[122:123]
	v_pk_mul_f32 v[114:115], v[114:115], v[150:151]
	v_mov_b32_e32 v150, v112
	v_mov_b32_e32 v153, v115
	v_mov_b32_e32 v151, v114
	v_pk_mul_f32 v[152:153], v[152:153], v[152:153]
	v_pk_fma_f32 v[122:123], v[10:11], v[148:149], v[122:123]
	v_pk_fma_f32 v[150:151], v[150:151], v[150:151], v[152:153]
	v_lshlrev_b32_e32 v152, 16, v93
	v_add_f32_e32 v159, v150, v151
	v_lshlrev_b32_e32 v150, 16, v92
	v_and_b32_e32 v151, 0xffff0000, v92
	v_pk_fma_f32 v[120:121], v[12:13], v[150:151], v[120:121]
	v_pk_fma_f32 v[116:117], v[16:17], v[150:151], v[116:117]
	v_pk_fma_f32 v[120:121], v[16:17], v[124:125], v[120:121]
	v_pk_mul_f32 v[124:125], v[120:121], v[222:223] op_sel_hi:[1,0]
	v_pk_mul_f32 v[154:155], v[116:117], v[222:223] op_sel_hi:[1,0]
	v_exp_f32_e32 v124, v124
	v_exp_f32_e32 v125, v125
	v_exp_f32_e32 v154, v154
	v_exp_f32_e32 v155, v155
	v_pk_add_f32 v[124:125], v[124:125], 1.0 op_sel_hi:[1,0]
	v_pk_add_f32 v[154:155], v[154:155], 1.0 op_sel_hi:[1,0]
	v_rcp_f32_e32 v124, v124
	v_rcp_f32_e32 v125, v125
	v_and_b32_e32 v153, 0xffff0000, v93
	v_rcp_f32_e32 v154, v154
	v_rcp_f32_e32 v155, v155
	v_pk_fma_f32 v[118:119], v[10:11], v[126:127], v[118:119]
	v_pk_fma_f32 v[122:123], v[14:15], v[152:153], v[122:123]
	v_lshlrev_b32_e32 v126, 16, v95
	v_and_b32_e32 v127, 0xffff0000, v95
	v_pk_fma_f32 v[118:119], v[14:15], v[148:149], v[118:119]
	v_pk_fma_f32 v[122:123], v[18:19], v[126:127], v[122:123]
	v_pk_fma_f32 v[118:119], v[18:19], v[152:153], v[118:119]
	v_pk_mul_f32 v[120:121], v[120:121], v[124:125]
	v_pk_mul_f32 v[124:125], v[122:123], v[222:223] op_sel_hi:[1,0]
	v_pk_mul_f32 v[116:117], v[116:117], v[154:155]
	v_pk_mul_f32 v[154:155], v[118:119], v[222:223] op_sel_hi:[1,0]
	v_exp_f32_e32 v124, v124
	v_exp_f32_e32 v125, v125
	v_exp_f32_e32 v154, v154
	v_exp_f32_e32 v155, v155
	v_pk_add_f32 v[124:125], v[124:125], 1.0 op_sel_hi:[1,0]
	v_pk_add_f32 v[154:155], v[154:155], 1.0 op_sel_hi:[1,0]
	v_rcp_f32_e32 v124, v124
	v_rcp_f32_e32 v125, v125
	v_rcp_f32_e32 v154, v154
	v_rcp_f32_e32 v155, v155
	v_mov_b32_e32 v126, v121
	v_pk_mul_f32 v[122:123], v[122:123], v[124:125]
	v_mov_b32_e32 v156, v117
	v_pk_mul_f32 v[118:119], v[118:119], v[154:155]
	v_mov_b32_e32 v127, v123
	v_mov_b32_e32 v157, v119
	v_mov_b32_e32 v124, v120
	v_mov_b32_e32 v125, v122
	v_pk_mul_f32 v[126:127], v[126:127], v[126:127]
	v_mov_b32_e32 v154, v116
	v_mov_b32_e32 v155, v118
	v_pk_mul_f32 v[156:157], v[156:157], v[156:157]
	v_pk_fma_f32 v[124:125], v[124:125], v[124:125], v[126:127]
	v_pk_fma_f32 v[154:155], v[154:155], v[154:155], v[156:157]
	v_add_f32_e32 v124, v124, v125
	v_lshlrev_b32_e32 v125, 2, v133
	v_add_f32_e32 v154, v154, v155
	s_nop 1
	v_add_f32_dpp v127, v134, v134 quad_perm:[1,0,3,2] row_mask:0xf bank_mask:0xf
	v_add_f32_dpp v134, v135, v135 quad_perm:[1,0,3,2] row_mask:0xf bank_mask:0xf
	v_add_f32_dpp v135, v136, v136 quad_perm:[1,0,3,2] row_mask:0xf bank_mask:0xf
	v_add_f32_dpp v136, v137, v137 quad_perm:[1,0,3,2] row_mask:0xf bank_mask:0xf
	v_add_f32_dpp v137, v138, v138 quad_perm:[1,0,3,2] row_mask:0xf bank_mask:0xf
	v_add_f32_dpp v138, v139, v139 quad_perm:[1,0,3,2] row_mask:0xf bank_mask:0xf
	v_add_f32_dpp v139, v140, v140 quad_perm:[1,0,3,2] row_mask:0xf bank_mask:0xf
	v_add_f32_dpp v140, v141, v141 quad_perm:[1,0,3,2] row_mask:0xf bank_mask:0xf
	v_add_f32_dpp v141, v142, v142 quad_perm:[1,0,3,2] row_mask:0xf bank_mask:0xf
	v_add_f32_dpp v142, v143, v143 quad_perm:[1,0,3,2] row_mask:0xf bank_mask:0xf
	v_add_f32_dpp v143, v144, v144 quad_perm:[1,0,3,2] row_mask:0xf bank_mask:0xf
	v_add_f32_dpp v144, v145, v145 quad_perm:[1,0,3,2] row_mask:0xf bank_mask:0xf
	v_add_f32_dpp v145, v158, v158 quad_perm:[1,0,3,2] row_mask:0xf bank_mask:0xf
	v_add_f32_dpp v146, v159, v159 quad_perm:[1,0,3,2] row_mask:0xf bank_mask:0xf
	v_add_f32_dpp v147, v154, v154 quad_perm:[1,0,3,2] row_mask:0xf bank_mask:0xf
	v_add_f32_dpp v124, v124, v124 quad_perm:[1,0,3,2] row_mask:0xf bank_mask:0xf
	v_add_f32_dpp v127, v127, v127 quad_perm:[2,3,0,1] row_mask:0xf bank_mask:0xf
	v_add_f32_dpp v134, v134, v134 quad_perm:[2,3,0,1] row_mask:0xf bank_mask:0xf
	v_add_f32_dpp v135, v135, v135 quad_perm:[2,3,0,1] row_mask:0xf bank_mask:0xf
	v_add_f32_dpp v136, v136, v136 quad_perm:[2,3,0,1] row_mask:0xf bank_mask:0xf
	v_add_f32_dpp v137, v137, v137 quad_perm:[2,3,0,1] row_mask:0xf bank_mask:0xf
	v_add_f32_dpp v138, v138, v138 quad_perm:[2,3,0,1] row_mask:0xf bank_mask:0xf
	v_add_f32_dpp v139, v139, v139 quad_perm:[2,3,0,1] row_mask:0xf bank_mask:0xf
	v_add_f32_dpp v140, v140, v140 quad_perm:[2,3,0,1] row_mask:0xf bank_mask:0xf
	v_add_f32_dpp v141, v141, v141 quad_perm:[2,3,0,1] row_mask:0xf bank_mask:0xf
	v_add_f32_dpp v142, v142, v142 quad_perm:[2,3,0,1] row_mask:0xf bank_mask:0xf
	v_add_f32_dpp v143, v143, v143 quad_perm:[2,3,0,1] row_mask:0xf bank_mask:0xf
	v_add_f32_dpp v144, v144, v144 quad_perm:[2,3,0,1] row_mask:0xf bank_mask:0xf
	v_add_f32_dpp v145, v145, v145 quad_perm:[2,3,0,1] row_mask:0xf bank_mask:0xf
	v_add_f32_dpp v146, v146, v146 quad_perm:[2,3,0,1] row_mask:0xf bank_mask:0xf
	v_add_f32_dpp v147, v147, v147 quad_perm:[2,3,0,1] row_mask:0xf bank_mask:0xf
	v_add_f32_dpp v124, v124, v124 quad_perm:[2,3,0,1] row_mask:0xf bank_mask:0xf
	v_add_f32_dpp v127, v127, v127 row_half_mirror row_mask:0xf bank_mask:0xf
	v_add_f32_dpp v134, v134, v134 row_half_mirror row_mask:0xf bank_mask:0xf
	v_add_f32_dpp v135, v135, v135 row_half_mirror row_mask:0xf bank_mask:0xf
	v_add_f32_dpp v136, v136, v136 row_half_mirror row_mask:0xf bank_mask:0xf
	v_add_f32_dpp v124, v124, v124 row_half_mirror row_mask:0xf bank_mask:0xf
	v_add_f32_dpp v137, v137, v137 row_half_mirror row_mask:0xf bank_mask:0xf
	v_add_f32_dpp v138, v138, v138 row_half_mirror row_mask:0xf bank_mask:0xf
	v_add_f32_dpp v139, v139, v139 row_half_mirror row_mask:0xf bank_mask:0xf
	v_add_f32_dpp v140, v140, v140 row_half_mirror row_mask:0xf bank_mask:0xf
	v_add_f32_dpp v141, v141, v141 row_half_mirror row_mask:0xf bank_mask:0xf
	v_add_f32_dpp v142, v142, v142 row_half_mirror row_mask:0xf bank_mask:0xf
	v_add_f32_dpp v143, v143, v143 row_half_mirror row_mask:0xf bank_mask:0xf
	v_add_f32_dpp v144, v144, v144 row_half_mirror row_mask:0xf bank_mask:0xf
	v_add_f32_dpp v145, v145, v145 row_half_mirror row_mask:0xf bank_mask:0xf
	v_add_f32_dpp v146, v146, v146 row_half_mirror row_mask:0xf bank_mask:0xf
	v_add_f32_dpp v147, v147, v147 row_half_mirror row_mask:0xf bank_mask:0xf
	v_add_f32_dpp v127, v127, v127 row_mirror row_mask:0xf bank_mask:0xf
	v_xor_b32_e32 v125, 64, v125
	v_add_f32_dpp v134, v134, v134 row_mirror row_mask:0xf bank_mask:0xf
	v_add_f32_dpp v135, v135, v135 row_mirror row_mask:0xf bank_mask:0xf
	v_add_f32_dpp v136, v136, v136 row_mirror row_mask:0xf bank_mask:0xf
	v_add_f32_dpp v137, v137, v137 row_mirror row_mask:0xf bank_mask:0xf
	v_add_f32_dpp v138, v138, v138 row_mirror row_mask:0xf bank_mask:0xf
	v_add_f32_dpp v139, v139, v139 row_mirror row_mask:0xf bank_mask:0xf
	v_add_f32_dpp v140, v140, v140 row_mirror row_mask:0xf bank_mask:0xf
	v_add_f32_dpp v141, v141, v141 row_mirror row_mask:0xf bank_mask:0xf
	v_add_f32_dpp v142, v142, v142 row_mirror row_mask:0xf bank_mask:0xf
	v_add_f32_dpp v143, v143, v143 row_mirror row_mask:0xf bank_mask:0xf
	v_add_f32_dpp v144, v144, v144 row_mirror row_mask:0xf bank_mask:0xf
	v_add_f32_dpp v145, v145, v145 row_mirror row_mask:0xf bank_mask:0xf
	v_add_f32_dpp v146, v146, v146 row_mirror row_mask:0xf bank_mask:0xf
	v_add_f32_dpp v147, v147, v147 row_mirror row_mask:0xf bank_mask:0xf
	v_add_f32_dpp v124, v124, v124 row_mirror row_mask:0xf bank_mask:0xf
	ds_bpermute_b32 v126, v125, v127
	ds_bpermute_b32 v148, v125, v134
	ds_bpermute_b32 v149, v125, v135
	ds_bpermute_b32 v150, v125, v136
	ds_bpermute_b32 v151, v125, v137
	ds_bpermute_b32 v152, v125, v138
	ds_bpermute_b32 v153, v125, v139
	ds_bpermute_b32 v154, v125, v140
	ds_bpermute_b32 v155, v125, v141
	ds_bpermute_b32 v156, v125, v142
	ds_bpermute_b32 v157, v125, v143
	ds_bpermute_b32 v158, v125, v144
	ds_bpermute_b32 v159, v125, v145
	ds_bpermute_b32 v160, v125, v146
	ds_bpermute_b32 v162, v125, v147
	ds_bpermute_b32 v125, v125, v124
	s_waitcnt lgkmcnt(14)
	v_add_f32_e32 v126, v127, v126
	v_cmp_gt_u32_e32 vcc, 32, v133
	v_add_f32_e32 v127, v134, v148
	s_waitcnt lgkmcnt(13)
	v_add_f32_e32 v134, v135, v149
	s_waitcnt lgkmcnt(0)
	v_add_f32_e32 v125, v124, v125
	v_add_f32_e32 v124, 0x358637bd, v126
	v_rsq_f32_e32 v124, v124
	v_cndmask_b32_e32 v133, 1.0, v189, vcc
	v_add_f32_e32 v135, v136, v150
	v_add_f32_e32 v136, v137, v151
	v_mul_f32_e32 v124, v133, v124
	v_pk_mul_f32 v[26:27], v[26:27], v[124:125] op_sel_hi:[1,0]
	v_pk_mul_f32 v[24:25], v[24:25], v[124:125] op_sel_hi:[1,0]
	v_add_f32_e32 v124, 0x358637bd, v127
	v_rsq_f32_e32 v124, v124
	v_add_f32_e32 v137, v138, v152
	v_add_f32_e32 v138, v139, v153
	v_add_f32_e32 v139, v140, v154
	v_mul_f32_e32 v124, v133, v124
	v_pk_mul_f32 v[34:35], v[34:35], v[124:125] op_sel_hi:[1,0]
	v_pk_mul_f32 v[28:29], v[28:29], v[124:125] op_sel_hi:[1,0]
	v_add_f32_e32 v124, 0x358637bd, v134
	v_rsq_f32_e32 v124, v124
	v_add_f32_e32 v140, v141, v155
	v_add_f32_e32 v141, v142, v156
	v_add_f32_e32 v142, v143, v157
	v_mul_f32_e32 v124, v133, v124
	v_pk_mul_f32 v[42:43], v[42:43], v[124:125] op_sel_hi:[1,0]
	v_pk_mul_f32 v[36:37], v[36:37], v[124:125] op_sel_hi:[1,0]
	v_add_f32_e32 v124, 0x358637bd, v135
	v_rsq_f32_e32 v124, v124
	v_add_f32_e32 v143, v144, v158
	v_add_f32_e32 v144, v145, v159
	v_add_f32_e32 v145, v146, v160
	v_mul_f32_e32 v124, v133, v124
	v_pk_mul_f32 v[46:47], v[46:47], v[124:125] op_sel_hi:[1,0]
	v_pk_mul_f32 v[44:45], v[44:45], v[124:125] op_sel_hi:[1,0]
	v_add_f32_e32 v124, 0x358637bd, v136
	v_rsq_f32_e32 v124, v124
	v_add_f32_e32 v146, v147, v162
	s_movk_i32 s8, 0x4400
	v_cvt_pk_bf16_f32 v24, v24, v25
	v_mul_f32_e32 v124, v133, v124
	v_pk_mul_f32 v[54:55], v[54:55], v[124:125] op_sel_hi:[1,0]
	v_pk_mul_f32 v[52:53], v[52:53], v[124:125] op_sel_hi:[1,0]
	v_add_f32_e32 v124, 0x358637bd, v137
	v_rsq_f32_e32 v124, v124
	v_cvt_pk_bf16_f32 v25, v26, v27
	v_cvt_pk_bf16_f32 v26, v28, v29
	v_cvt_pk_bf16_f32 v27, v34, v35
	v_mul_f32_e32 v124, v133, v124
	v_pk_mul_f32 v[58:59], v[58:59], v[124:125] op_sel_hi:[1,0]
	v_pk_mul_f32 v[56:57], v[56:57], v[124:125] op_sel_hi:[1,0]
	v_add_f32_e32 v124, 0x358637bd, v138
	v_rsq_f32_e32 v124, v124
	s_nop 0
	v_mul_f32_e32 v124, v133, v124
	v_pk_mul_f32 v[50:51], v[50:51], v[124:125] op_sel_hi:[1,0]
	v_pk_mul_f32 v[48:49], v[48:49], v[124:125] op_sel_hi:[1,0]
	v_add_f32_e32 v124, 0x358637bd, v139
	v_rsq_f32_e32 v124, v124
	s_nop 0
	v_mul_f32_e32 v124, v133, v124
	v_pk_mul_f32 v[40:41], v[40:41], v[124:125] op_sel_hi:[1,0]
	v_pk_mul_f32 v[38:39], v[38:39], v[124:125] op_sel_hi:[1,0]
	v_add_f32_e32 v124, 0x358637bd, v140
	v_rsq_f32_e32 v124, v124
	s_nop 0
	v_mul_f32_e32 v124, v133, v124
	v_pk_mul_f32 v[32:33], v[32:33], v[124:125] op_sel_hi:[1,0]
	v_pk_mul_f32 v[30:31], v[30:31], v[124:125] op_sel_hi:[1,0]
	v_add_f32_e32 v124, 0x358637bd, v141
	v_rsq_f32_e32 v124, v124
	s_nop 0
	v_mul_f32_e32 v124, v133, v124
	v_pk_mul_f32 v[22:23], v[22:23], v[124:125] op_sel_hi:[1,0]
	v_pk_mul_f32 v[20:21], v[20:21], v[124:125] op_sel_hi:[1,0]
	v_add_f32_e32 v124, 0x358637bd, v142
	v_rsq_f32_e32 v124, v124
	v_cvt_pk_bf16_f32 v20, v20, v21
	v_cvt_pk_bf16_f32 v21, v22, v23
	v_mul_f32_e32 v124, v133, v124
	v_pk_mul_f32 v[62:63], v[62:63], v[124:125] op_sel_hi:[1,0]
	v_pk_mul_f32 v[60:61], v[60:61], v[124:125] op_sel_hi:[1,0]
	v_add_f32_e32 v124, 0x358637bd, v143
	v_rsq_f32_e32 v124, v124
	s_nop 0
	v_mul_f32_e32 v124, v133, v124
	v_pk_mul_f32 v[106:107], v[106:107], v[124:125] op_sel_hi:[1,0]
	v_pk_mul_f32 v[104:105], v[104:105], v[124:125] op_sel_hi:[1,0]
	v_add_f32_e32 v124, 0x358637bd, v144
	v_rsq_f32_e32 v124, v124
	v_cvt_pk_bf16_f32 v22, v104, v105
	v_cvt_pk_bf16_f32 v23, v106, v107
	v_mul_f32_e32 v124, v133, v124
	v_pk_mul_f32 v[110:111], v[110:111], v[124:125] op_sel_hi:[1,0]
	v_pk_mul_f32 v[108:109], v[108:109], v[124:125] op_sel_hi:[1,0]
	v_add_f32_e32 v124, 0x358637bd, v145
	v_rsq_f32_e32 v124, v124
	s_nop 0
	v_mul_f32_e32 v124, v133, v124
	v_pk_mul_f32 v[114:115], v[114:115], v[124:125] op_sel_hi:[1,0]
	v_pk_mul_f32 v[112:113], v[112:113], v[124:125] op_sel_hi:[1,0]
	v_add_f32_e32 v124, 0x358637bd, v146
	v_rsq_f32_e32 v124, v124
	s_nop 0
	v_mul_f32_e32 v124, v133, v124
	v_pk_mul_f32 v[118:119], v[118:119], v[124:125] op_sel_hi:[1,0]
	v_pk_mul_f32 v[116:117], v[116:117], v[124:125] op_sel_hi:[1,0]
	v_add_f32_e32 v124, 0x358637bd, v125
	v_rsq_f32_e32 v124, v124
	s_nop 0
	v_mul_f32_e32 v124, v133, v124
	v_pk_mul_f32 v[122:123], v[122:123], v[124:125] op_sel_hi:[1,0]
	v_pk_mul_f32 v[120:121], v[120:121], v[124:125] op_sel_hi:[1,0]
	v_mul_lo_u32 v124, v131, s8
	v_add_u32_e32 v124, 0, v124
	v_readlane_b32 s8, v220, 40
	s_nop 1
	v_add3_u32 v124, v124, v132, s8
	ds_write2_b64 v124, v[24:25], v[26:27] offset1:34
	v_cvt_pk_bf16_f32 v24, v36, v37
	v_cvt_pk_bf16_f32 v25, v42, v43
	v_cvt_pk_bf16_f32 v26, v44, v45
	v_cvt_pk_bf16_f32 v27, v46, v47
	ds_write2_b64 v124, v[24:25], v[26:27] offset0:68 offset1:102
	v_cvt_pk_bf16_f32 v24, v52, v53
	v_cvt_pk_bf16_f32 v25, v54, v55
	v_cvt_pk_bf16_f32 v26, v56, v57
	v_cvt_pk_bf16_f32 v27, v58, v59
	ds_write2_b64 v124, v[24:25], v[26:27] offset0:136 offset1:170
	v_cvt_pk_bf16_f32 v24, v48, v49
	v_cvt_pk_bf16_f32 v25, v50, v51
	v_cvt_pk_bf16_f32 v26, v38, v39
	v_cvt_pk_bf16_f32 v27, v40, v41
	ds_write2_b64 v124, v[24:25], v[26:27] offset0:204 offset1:238
	v_cvt_pk_bf16_f32 v24, v30, v31
	v_cvt_pk_bf16_f32 v25, v32, v33
	v_add_u32_e32 v26, 0x800, v124
	ds_write2_b64 v26, v[24:25], v[20:21] offset0:16 offset1:50
	v_cvt_pk_bf16_f32 v20, v60, v61
	v_cvt_pk_bf16_f32 v21, v62, v63
	ds_write2_b64 v26, v[20:21], v[22:23] offset0:84 offset1:118
	v_cvt_pk_bf16_f32 v20, v108, v109
	v_cvt_pk_bf16_f32 v21, v110, v111
	v_cvt_pk_bf16_f32 v22, v112, v113
	v_cvt_pk_bf16_f32 v23, v114, v115
	ds_write2_b64 v26, v[20:21], v[22:23] offset0:152 offset1:186
	v_cvt_pk_bf16_f32 v20, v116, v117
	v_cvt_pk_bf16_f32 v21, v118, v119
	v_cvt_pk_bf16_f32 v22, v120, v121
	v_cvt_pk_bf16_f32 v23, v122, v123
	ds_write2_b64 v26, v[20:21], v[22:23] offset0:220 offset1:254
	s_branch .LBB0_403

; #define LAS __attribute__((address_space(3)))
; __device__ __forceinline__ void gdn_prep_phase(const Frame& F0, const Args& a0, int l) {
;     ...
;             if (tid2 < 128) { const int d = tid2 >> 6, bi = (tid2 >> 4) & 3, col = tid2 & 15;
;                 const LAS unsigned char* Ab = lds + GD_AD + d * 17408 + (16 * bi) * GD_PITCH + (16 * bi) * 4; LAS unsigned char* Mb = lds + GD_MD + d * 17408 + (16 * bi) * GD_PITCH + (16 * bi) * 4;
;                 float x[16];
; #pragma unroll
;                 for (int r = 0; r < 16; ++r) { float acc = (r == col) ? 1.f : 0.f;
;                     f32x4 av[4];
; #pragma unroll
;                     for (int q4 = 0; q4 < 4; ++q4) if (4 * q4 < r) av[q4] = *(const LAS f32x4*)(Ab + r * GD_PITCH + q4 * 16);
; #pragma unroll
;                     for (int j = 0; j < 16; ++j) if (j < r) acc -= av[j >> 2][j & 3] * x[j];
;                     x[r] = acc; *(LAS float*)(Mb + r * GD_PITCH + col * 4) = acc; }
.LBB0_438:
	v_mbcnt_lo_u32_b32 v108, -1, 0
	v_mbcnt_hi_u32_b32 v108, -1, v108
	s_movk_i32 s10, 0x80
	v_add_u32_e32 v36, s23, v108
	v_and_b32_e32 v109, 15, v108
	v_cmp_gt_i32_e32 vcc, s10, v36
	v_lshlrev_b32_e32 v20, 2, v109
	s_and_saveexec_b64 s[10:11], vcc
	s_cbranch_execz .LBB0_440
	v_lshrrev_b32_e32 v21, 6, v36
	s_movk_i32 s14, 0x4400
	v_and_b32_e32 v22, 48, v108
	v_mul_lo_u32 v21, v21, s14
	v_add_u32_e32 v23, 0, v21
	v_mul_u32_u24_e32 v24, 0x110, v22
	v_lshlrev_b32_e32 v22, 2, v22
	v_readlane_b32 s14, v220, 12
	v_add3_u32 v34, v23, v24, v22
	v_cmp_eq_u32_e32 vcc, 0, v109
	v_add3_u32 v21, s14, v21, v24
	v_add3_u32 v21, v21, v22, v20
	v_add_u32_e32 v212, 0x400, v21
	v_add_u32_e32 v213, 0x800, v21
	v_add_u32_e32 v214, 0xc00, v21
	ds_read_b128 v[196:199], v34 offset:52496
	ds_read_b128 v[164:167], v34 offset:52768
	v_cmp_eq_u32_e32 vcc, 0, v109
	s_nop 1
	v_cndmask_b32_e64 v224, 0, 1.0, vcc
	ds_read_b128 v[240:243], v34 offset:53040
	v_cmp_eq_u32_e32 vcc, 1, v109
	s_nop 1
	v_cndmask_b32_e64 v216, 0, 1.0, vcc
	s_waitcnt lgkmcnt(2)
	v_fma_f32 v225, -v224, v196, v216
	ds_write2_b32 v21, v224, v225 offset0:0 offset1:68
	ds_read_b128 v[196:199], v34 offset:53312
	v_cmp_eq_u32_e32 vcc, 2, v109
	s_nop 1
	v_cndmask_b32_e64 v216, 0, 1.0, vcc
	s_waitcnt lgkmcnt(3)
	v_fma_f32 v216, -v224, v164, v216
	v_fma_f32 v226, -v225, v165, v216
	ds_read_b128 v[164:167], v34 offset:53584
	ds_read_b128 v[168:171], v34 offset:53600
	v_cmp_eq_u32_e32 vcc, 3, v109
	s_nop 1
	v_cndmask_b32_e64 v216, 0, 1.0, vcc
	s_waitcnt lgkmcnt(4)
	v_fma_f32 v216, -v224, v240, v216
	v_fma_f32 v216, -v225, v241, v216
	v_fma_f32 v227, -v226, v242, v216
	ds_write2_b32 v21, v226, v227 offset0:136 offset1:204
	ds_read_b128 v[240:243], v34 offset:53856
	ds_read_b128 v[244:247], v34 offset:53872
	v_cmp_eq_u32_e32 vcc, 4, v109
	s_nop 1
	v_cndmask_b32_e64 v216, 0, 1.0, vcc
	s_waitcnt lgkmcnt(5)
	v_fma_f32 v216, -v224, v196, v216
	v_fma_f32 v216, -v225, v197, v216
	v_fma_f32 v216, -v226, v198, v216
	v_fma_f32 v228, -v227, v199, v216
	ds_read_b128 v[196:199], v34 offset:54128
	ds_read_b128 v[200:203], v34 offset:54144
	v_cmp_eq_u32_e32 vcc, 5, v109
	s_nop 1
	v_cndmask_b32_e64 v216, 0, 1.0, vcc
	s_waitcnt lgkmcnt(5)
	v_fma_f32 v216, -v224, v164, v216
	v_fma_f32 v216, -v225, v165, v216
	v_fma_f32 v216, -v226, v166, v216
	v_fma_f32 v216, -v227, v167, v216
	v_fma_f32 v229, -v228, v168, v216
	ds_write2_b32 v212, v228, v229 offset0:16 offset1:84
	ds_read_b128 v[164:167], v34 offset:54400
	ds_read_b128 v[168:171], v34 offset:54416
	v_cmp_eq_u32_e32 vcc, 6, v109
	s_nop 1
	v_cndmask_b32_e64 v216, 0, 1.0, vcc
	s_waitcnt lgkmcnt(5)
	v_fma_f32 v216, -v224, v240, v216
	v_fma_f32 v216, -v225, v241, v216
	v_fma_f32 v216, -v226, v242, v216
	v_fma_f32 v216, -v227, v243, v216
	v_fma_f32 v216, -v228, v244, v216
	v_fma_f32 v230, -v229, v245, v216
	ds_read_b128 v[240:243], v34 offset:54672
	ds_read_b128 v[244:247], v34 offset:54688
	ds_read_b128 v[248:251], v34 offset:54704
	v_cmp_eq_u32_e32 vcc, 7, v109
	s_nop 1
	v_cndmask_b32_e64 v216, 0, 1.0, vcc
	s_waitcnt lgkmcnt(6)
	v_fma_f32 v216, -v224, v196, v216
	v_fma_f32 v216, -v225, v197, v216
	v_fma_f32 v216, -v226, v198, v216
	v_fma_f32 v216, -v227, v199, v216
	v_fma_f32 v216, -v228, v200, v216
	v_fma_f32 v216, -v229, v201, v216
	v_fma_f32 v231, -v230, v202, v216
	ds_write2_b32 v212, v230, v231 offset0:152 offset1:220
	ds_read_b128 v[196:199], v34 offset:54944
	ds_read_b128 v[200:203], v34 offset:54960
	ds_read_b128 v[204:207], v34 offset:54976
	v_cmp_eq_u32_e32 vcc, 8, v109
	s_nop 1
	v_cndmask_b32_e64 v216, 0, 1.0, vcc
	s_waitcnt lgkmcnt(7)
	v_fma_f32 v216, -v224, v164, v216
	v_fma_f32 v216, -v225, v165, v216
	v_fma_f32 v216, -v226, v166, v216
	v_fma_f32 v216, -v227, v167, v216
	v_fma_f32 v216, -v228, v168, v216
	v_fma_f32 v216, -v229, v169, v216
	v_fma_f32 v216, -v230, v170, v216
	v_fma_f32 v232, -v231, v171, v216
	ds_read_b128 v[164:167], v34 offset:55216
	ds_read_b128 v[168:171], v34 offset:55232
	ds_read_b128 v[172:175], v34 offset:55248
	v_cmp_eq_u32_e32 vcc, 9, v109
	s_nop 1
	v_cndmask_b32_e64 v216, 0, 1.0, vcc
	s_waitcnt lgkmcnt(7)
; #define LAS __attribute__((address_space(3)))
; __device__ __forceinline__ void gdn_prep_phase(const Frame& F0, const Args& a0, int l) {
;     ...
;             if (tid2 < 128) { const int d = tid2 >> 6, bi = (tid2 >> 4) & 3, col = tid2 & 15;
;                 const LAS unsigned char* Ab = lds + GD_AD + d * 17408 + (16 * bi) * GD_PITCH + (16 * bi) * 4; LAS unsigned char* Mb = lds + GD_MD + d * 17408 + (16 * bi) * GD_PITCH + (16 * bi) * 4;
;                 float x[16];
; #pragma unroll
;                 for (int r = 0; r < 16; ++r) { float acc = (r == col) ? 1.f : 0.f;
;                     f32x4 av[4];
; #pragma unroll
;                     for (int q4 = 0; q4 < 4; ++q4) if (4 * q4 < r) av[q4] = *(const LAS f32x4*)(Ab + r * GD_PITCH + q4 * 16);
; #pragma unroll
;                     for (int j = 0; j < 16; ++j) if (j < r) acc -= av[j >> 2][j & 3] * x[j];
;                     x[r] = acc; *(LAS float*)(Mb + r * GD_PITCH + col * 4) = acc; }
	v_fma_f32 v216, -v224, v240, v216
	v_fma_f32 v216, -v225, v241, v216
	v_fma_f32 v216, -v226, v242, v216
	v_fma_f32 v216, -v227, v243, v216
	v_fma_f32 v216, -v228, v244, v216
	v_fma_f32 v216, -v229, v245, v216
	v_fma_f32 v216, -v230, v246, v216
	v_fma_f32 v216, -v231, v247, v216
	v_fma_f32 v233, -v232, v248, v216
	ds_write2_b32 v213, v232, v233 offset0:32 offset1:100
	ds_read_b128 v[240:243], v34 offset:55488
	ds_read_b128 v[244:247], v34 offset:55504
	ds_read_b128 v[248:251], v34 offset:55520
	v_cmp_eq_u32_e32 vcc, 10, v109
	s_nop 1
	v_cndmask_b32_e64 v216, 0, 1.0, vcc
	s_waitcnt lgkmcnt(7)
	v_fma_f32 v216, -v224, v196, v216
	v_fma_f32 v216, -v225, v197, v216
	v_fma_f32 v216, -v226, v198, v216
	v_fma_f32 v216, -v227, v199, v216
	v_fma_f32 v216, -v228, v200, v216
	v_fma_f32 v216, -v229, v201, v216
	v_fma_f32 v216, -v230, v202, v216
	v_fma_f32 v216, -v231, v203, v216
	v_fma_f32 v216, -v232, v204, v216
	v_fma_f32 v234, -v233, v205, v216
	ds_read_b128 v[196:199], v34 offset:55760
	ds_read_b128 v[200:203], v34 offset:55776
	ds_read_b128 v[204:207], v34 offset:55792
	ds_read_b128 v[208:211], v34 offset:55808
	v_cmp_eq_u32_e32 vcc, 11, v109
	s_nop 1
	v_cndmask_b32_e64 v216, 0, 1.0, vcc
	s_waitcnt lgkmcnt(8)
	v_fma_f32 v216, -v224, v164, v216
	v_fma_f32 v216, -v225, v165, v216
	v_fma_f32 v216, -v226, v166, v216
	v_fma_f32 v216, -v227, v167, v216
	v_fma_f32 v216, -v228, v168, v216
	v_fma_f32 v216, -v229, v169, v216
	v_fma_f32 v216, -v230, v170, v216
	v_fma_f32 v216, -v231, v171, v216
	v_fma_f32 v216, -v232, v172, v216
	v_fma_f32 v216, -v233, v173, v216
	v_fma_f32 v235, -v234, v174, v216
	ds_write2_b32 v213, v234, v235 offset0:168 offset1:236
	ds_read_b128 v[164:167], v34 offset:56032
	ds_read_b128 v[168:171], v34 offset:56048
	ds_read_b128 v[172:175], v34 offset:56064
	ds_read_b128 v[176:179], v34 offset:56080
	v_cmp_eq_u32_e32 vcc, 12, v109
	s_nop 1
	v_cndmask_b32_e64 v216, 0, 1.0, vcc
	s_waitcnt lgkmcnt(9)
	v_fma_f32 v216, -v224, v240, v216
	v_fma_f32 v216, -v225, v241, v216
	v_fma_f32 v216, -v226, v242, v216
	v_fma_f32 v216, -v227, v243, v216
	v_fma_f32 v216, -v228, v244, v216
	v_fma_f32 v216, -v229, v245, v216
	v_fma_f32 v216, -v230, v246, v216
	v_fma_f32 v216, -v231, v247, v216
	v_fma_f32 v216, -v232, v248, v216
	v_fma_f32 v216, -v233, v249, v216
	v_fma_f32 v216, -v234, v250, v216
	v_fma_f32 v236, -v235, v251, v216
	ds_read_b128 v[240:243], v34 offset:56304
	ds_read_b128 v[244:247], v34 offset:56320
	ds_read_b128 v[248:251], v34 offset:56336
	ds_read_b128 v[252:255], v34 offset:56352
	v_cmp_eq_u32_e32 vcc, 13, v109
	s_nop 1
	v_cndmask_b32_e64 v216, 0, 1.0, vcc
	s_waitcnt lgkmcnt(9)
	v_fma_f32 v216, -v224, v196, v216
	v_fma_f32 v216, -v225, v197, v216
	v_fma_f32 v216, -v226, v198, v216
	v_fma_f32 v216, -v227, v199, v216
	v_fma_f32 v216, -v228, v200, v216
	v_fma_f32 v216, -v229, v201, v216
	v_fma_f32 v216, -v230, v202, v216
	v_fma_f32 v216, -v231, v203, v216
	v_fma_f32 v216, -v232, v204, v216
	v_fma_f32 v216, -v233, v205, v216
	v_fma_f32 v216, -v234, v206, v216
	v_fma_f32 v216, -v235, v207, v216
	v_fma_f32 v237, -v236, v208, v216
	ds_write2_b32 v214, v236, v237 offset0:48 offset1:116
	v_cmp_eq_u32_e32 vcc, 14, v109
	s_nop 1
	v_cndmask_b32_e64 v216, 0, 1.0, vcc
	s_waitcnt lgkmcnt(5)
	v_fma_f32 v216, -v224, v164, v216
	v_fma_f32 v216, -v225, v165, v216
	v_fma_f32 v216, -v226, v166, v216
	v_fma_f32 v216, -v227, v167, v216
	v_fma_f32 v216, -v228, v168, v216
	v_fma_f32 v216, -v229, v169, v216
	v_fma_f32 v216, -v230, v170, v216
	v_fma_f32 v216, -v231, v171, v216
	v_fma_f32 v216, -v232, v172, v216
	v_fma_f32 v216, -v233, v173, v216
	v_fma_f32 v216, -v234, v174, v216
	v_fma_f32 v216, -v235, v175, v216
	v_fma_f32 v216, -v236, v176, v216
	v_fma_f32 v238, -v237, v177, v216
	v_cmp_eq_u32_e32 vcc, 15, v109
	s_nop 1
	v_cndmask_b32_e64 v216, 0, 1.0, vcc
	s_waitcnt lgkmcnt(1)
	v_fma_f32 v216, -v224, v240, v216
	v_fma_f32 v216, -v225, v241, v216
	v_fma_f32 v216, -v226, v242, v216
	v_fma_f32 v216, -v227, v243, v216
	v_fma_f32 v216, -v228, v244, v216
	v_fma_f32 v216, -v229, v245, v216
	v_fma_f32 v216, -v230, v246, v216
	v_fma_f32 v216, -v231, v247, v216
	v_fma_f32 v216, -v232, v248, v216
	v_fma_f32 v216, -v233, v249, v216
	v_fma_f32 v216, -v234, v250, v216
	v_fma_f32 v216, -v235, v251, v216
	v_fma_f32 v216, -v236, v252, v216
	v_fma_f32 v216, -v237, v253, v216
	v_fma_f32 v239, -v238, v254, v216
	ds_write2_b32 v214, v238, v239 offset0:184 offset1:252
